# GEMM K-loop: exactly one memory op per MFMA gap (ds_write k in gap 2k, its refill load in gap 2k+1; the SIMD-pair partner shifted by one gap) instead of write+load in the same gap (variant of v49)
# baseline (speedup 1.0000x reference)
.LBB0_273:
	s_and_b32 s7, s6, 1
	s_mul_i32 s14, s7, 0xd800
	s_xor_b32 s7, s7, 1
	s_mul_i32 s7, s7, 0xd800
	s_add_i32 s6, s6, 1
	v_add_u32_e32 v186, s7, v146
	ds_read_b128 v[12:15], v189 offset:32
	ds_read_b128 v[24:27], v187 offset:36896
	ds_read_b128 v[16:19], v189 offset:4640
	ds_read_b128 v[28:31], v187 offset:41504
	ds_read_b128 v[20:23], v189 offset:9248
	ds_read_b128 v[48:51], v188 offset:32
	s_waitcnt lgkmcnt(10)
	v_mfma_f32_32x32x16_bf16 a[32:47], v[52:55], v[4:7], a[32:47]
	s_waitcnt vmcnt(11)
	ds_write_b128 v186, v[250:253]
	s_waitcnt lgkmcnt(9)
	v_mfma_f32_32x32x16_bf16 a[48:63], v[52:55], v[8:11], a[48:63]
	global_load_dwordx4 v[250:253], v254, s[100:101] offset:512
	v_mfma_f32_32x32x16_bf16 a[64:79], v[56:59], v[4:7], a[64:79]
	s_waitcnt vmcnt(11)
	ds_write_b128 v186, v[246:249] offset:4608
	v_mfma_f32_32x32x16_bf16 a[96:111], v[56:59], v[8:11], a[96:111]
	global_load_dwordx4 v[246:249], v205, s[100:101] offset:512
	s_waitcnt lgkmcnt(9)
	v_mfma_f32_32x32x16_bf16 a[80:95], v[60:63], v[4:7], a[80:95]
	s_waitcnt vmcnt(11)
	ds_write_b128 v186, v[242:245] offset:9216
	v_mfma_f32_32x32x16_bf16 a[112:127], v[60:63], v[8:11], a[112:127]
	global_load_dwordx4 v[242:245], v204, s[100:101] offset:512
	s_waitcnt lgkmcnt(9)
	v_mfma_f32_32x32x16_bf16 a[16:31], v[64:67], v[4:7], a[16:31]
	s_waitcnt vmcnt(11)
	ds_write_b128 v186, v[238:241] offset:13824
	v_mfma_f32_32x32x16_bf16 a[0:15], v[64:67], v[8:11], a[0:15]
	global_load_dwordx4 v[238:241], v203, s[100:101] offset:512
	ds_read_b128 v[52:55], v189 offset:64
	ds_read_b128 v[4:7], v187 offset:36928
	ds_read_b128 v[56:59], v189 offset:4672
	ds_read_b128 v[8:11], v187 offset:41536
	ds_read_b128 v[60:63], v189 offset:9280
	ds_read_b128 v[64:67], v188 offset:64
	s_waitcnt lgkmcnt(14)
	v_mfma_f32_32x32x16_bf16 a[32:47], v[12:15], v[24:27], a[32:47]
	s_waitcnt vmcnt(11)
	ds_write_b128 v186, v[234:237] offset:18432
	s_waitcnt lgkmcnt(13)
	v_mfma_f32_32x32x16_bf16 a[48:63], v[12:15], v[28:31], a[48:63]
	global_load_dwordx4 v[234:237], v202, s[100:101] offset:512
	v_mfma_f32_32x32x16_bf16 a[64:79], v[16:19], v[24:27], a[64:79]
	s_waitcnt vmcnt(11)
	ds_write_b128 v186, v[230:233] offset:23040
	v_mfma_f32_32x32x16_bf16 a[96:111], v[16:19], v[28:31], a[96:111]
	global_load_dwordx4 v[230:233], v201, s[100:101] offset:512
	s_waitcnt lgkmcnt(13)
	v_mfma_f32_32x32x16_bf16 a[80:95], v[20:23], v[24:27], a[80:95]
	s_waitcnt vmcnt(11)
	ds_write_b128 v186, v[226:229] offset:27648
	v_mfma_f32_32x32x16_bf16 a[112:127], v[20:23], v[28:31], a[112:127]
	global_load_dwordx4 v[226:229], v200, s[100:101] offset:512
	s_waitcnt lgkmcnt(13)
	v_mfma_f32_32x32x16_bf16 a[16:31], v[48:51], v[24:27], a[16:31]
	s_waitcnt vmcnt(11)
	ds_write_b128 v186, v[222:225] offset:32256
	v_mfma_f32_32x32x16_bf16 a[0:15], v[48:51], v[28:31], a[0:15]
	global_load_dwordx4 v[222:225], v199, s[100:101] offset:512
	ds_read_b128 v[12:15], v189 offset:96
	ds_read_b128 v[24:27], v187 offset:36960
	ds_read_b128 v[16:19], v189 offset:4704
	ds_read_b128 v[28:31], v187 offset:41568
	ds_read_b128 v[20:23], v189 offset:9312
	ds_read_b128 v[48:51], v188 offset:96
	s_waitcnt lgkmcnt(14)
	v_mfma_f32_32x32x16_bf16 a[32:47], v[52:55], v[4:7], a[32:47]
	s_waitcnt vmcnt(11)
	ds_write_b128 v186, v[218:221] offset:36864
	s_waitcnt lgkmcnt(13)
	v_mfma_f32_32x32x16_bf16 a[48:63], v[52:55], v[8:11], a[48:63]
	global_load_dwordx4 v[218:221], v198, s[98:99] offset:256
	v_mfma_f32_32x32x16_bf16 a[64:79], v[56:59], v[4:7], a[64:79]
	s_waitcnt vmcnt(11)
	ds_write_b128 v186, v[214:217] offset:41472
	v_mfma_f32_32x32x16_bf16 a[96:111], v[56:59], v[8:11], a[96:111]
	global_load_dwordx4 v[214:217], v197, s[98:99] offset:256
	s_waitcnt lgkmcnt(13)
	v_mfma_f32_32x32x16_bf16 a[80:95], v[60:63], v[4:7], a[80:95]
	s_waitcnt vmcnt(11)
	ds_write_b128 v186, v[210:213] offset:46080
	v_mfma_f32_32x32x16_bf16 a[112:127], v[60:63], v[8:11], a[112:127]
	global_load_dwordx4 v[210:213], v196, s[98:99] offset:256
	s_waitcnt lgkmcnt(13)
	v_mfma_f32_32x32x16_bf16 a[16:31], v[64:67], v[4:7], a[16:31]
	s_waitcnt vmcnt(11)
	ds_write_b128 v186, v[206:209] offset:50688
	v_mfma_f32_32x32x16_bf16 a[0:15], v[64:67], v[8:11], a[0:15]
	global_load_dwordx4 v[206:209], v195, s[98:99] offset:256
	s_add_u32 s100, s100, 0x80
	s_addc_u32 s101, s101, 0
	s_add_u32 s98, s98, 0x80
	s_addc_u32 s99, s99, 0
	s_waitcnt lgkmcnt(0)
	v_mfma_f32_32x32x16_bf16 a[32:47], v[12:15], v[24:27], a[32:47]
	v_mfma_f32_32x32x16_bf16 a[48:63], v[12:15], v[28:31], a[48:63]
	v_mfma_f32_32x32x16_bf16 a[64:79], v[16:19], v[24:27], a[64:79]
	v_mfma_f32_32x32x16_bf16 a[96:111], v[16:19], v[28:31], a[96:111]
	s_barrier
	v_add_u32_e32 v189, s7, v192
	v_add_u32_e32 v188, s7, v191
	v_add_u32_e32 v187, s7, v190
	ds_read_b128 v[52:55], v189
	ds_read_b128 v[4:7], v187 offset:36864
	ds_read_b128 v[56:59], v189 offset:4608
	ds_read_b128 v[8:11], v187 offset:41472
	ds_read_b128 v[60:63], v189 offset:9216
	ds_read_b128 v[64:67], v188
	v_mfma_f32_32x32x16_bf16 a[80:95], v[20:23], v[24:27], a[80:95]
	v_mfma_f32_32x32x16_bf16 a[112:127], v[20:23], v[28:31], a[112:127]
	v_mfma_f32_32x32x16_bf16 a[16:31], v[48:51], v[24:27], a[16:31]
	v_mfma_f32_32x32x16_bf16 a[0:15], v[48:51], v[28:31], a[0:15]
	s_add_u32 s2, s2, 0x80
	s_addc_u32 s3, s3, 0
	s_cmpk_lg_i32 s2, 0x700
	s_cbranch_scc1 .LBB0_273
	s_branch xg5_tail_1
xg5_varB_1:
	s_and_b32 s7, s6, 1
	s_mul_i32 s14, s7, 0xd800
	s_xor_b32 s7, s7, 1
	s_mul_i32 s7, s7, 0xd800
	s_add_i32 s6, s6, 1
	v_add_u32_e32 v186, s7, v146
	ds_read_b128 v[12:15], v189 offset:32
	ds_read_b128 v[24:27], v187 offset:36896
	ds_read_b128 v[16:19], v189 offset:4640
	ds_read_b128 v[28:31], v187 offset:41504
	ds_read_b128 v[20:23], v189 offset:9248
	ds_read_b128 v[48:51], v188 offset:32
	s_waitcnt lgkmcnt(10)
	v_mfma_f32_32x32x16_bf16 a[32:47], v[52:55], v[4:7], a[32:47]
	s_waitcnt lgkmcnt(8)
	v_mfma_f32_32x32x16_bf16 a[48:63], v[52:55], v[8:11], a[48:63]
	s_waitcnt vmcnt(11)
	ds_write_b128 v186, v[250:253]
	v_mfma_f32_32x32x16_bf16 a[64:79], v[56:59], v[4:7], a[64:79]
	global_load_dwordx4 v[250:253], v254, s[100:101] offset:512
	v_mfma_f32_32x32x16_bf16 a[96:111], v[56:59], v[8:11], a[96:111]
	s_waitcnt vmcnt(11)
	ds_write_b128 v186, v[246:249] offset:4608
	s_waitcnt lgkmcnt(9)
	v_mfma_f32_32x32x16_bf16 a[80:95], v[60:63], v[4:7], a[80:95]
	global_load_dwordx4 v[246:249], v205, s[100:101] offset:512
	v_mfma_f32_32x32x16_bf16 a[112:127], v[60:63], v[8:11], a[112:127]
	s_waitcnt vmcnt(11)
	ds_write_b128 v186, v[242:245] offset:9216
	s_waitcnt lgkmcnt(9)
	v_mfma_f32_32x32x16_bf16 a[16:31], v[64:67], v[4:7], a[16:31]
	global_load_dwordx4 v[242:245], v204, s[100:101] offset:512
	v_mfma_f32_32x32x16_bf16 a[0:15], v[64:67], v[8:11], a[0:15]
	s_waitcnt vmcnt(11)
	ds_write_b128 v186, v[238:241] offset:13824
	ds_read_b128 v[52:55], v189 offset:64
	ds_read_b128 v[4:7], v187 offset:36928
	ds_read_b128 v[56:59], v189 offset:4672
	ds_read_b128 v[8:11], v187 offset:41536
	ds_read_b128 v[60:63], v189 offset:9280
	ds_read_b128 v[64:67], v188 offset:64
	s_waitcnt lgkmcnt(14)
	v_mfma_f32_32x32x16_bf16 a[32:47], v[12:15], v[24:27], a[32:47]
	global_load_dwordx4 v[238:241], v203, s[100:101] offset:512
	s_waitcnt lgkmcnt(12)
	v_mfma_f32_32x32x16_bf16 a[48:63], v[12:15], v[28:31], a[48:63]
	s_waitcnt vmcnt(11)
	ds_write_b128 v186, v[234:237] offset:18432
	v_mfma_f32_32x32x16_bf16 a[64:79], v[16:19], v[24:27], a[64:79]
	global_load_dwordx4 v[234:237], v202, s[100:101] offset:512
	v_mfma_f32_32x32x16_bf16 a[96:111], v[16:19], v[28:31], a[96:111]
	s_waitcnt vmcnt(11)
	ds_write_b128 v186, v[230:233] offset:23040
	s_waitcnt lgkmcnt(13)
	v_mfma_f32_32x32x16_bf16 a[80:95], v[20:23], v[24:27], a[80:95]
	global_load_dwordx4 v[230:233], v201, s[100:101] offset:512
	v_mfma_f32_32x32x16_bf16 a[112:127], v[20:23], v[28:31], a[112:127]
	s_waitcnt vmcnt(11)
	ds_write_b128 v186, v[226:229] offset:27648
	s_waitcnt lgkmcnt(13)
	v_mfma_f32_32x32x16_bf16 a[16:31], v[48:51], v[24:27], a[16:31]
	global_load_dwordx4 v[226:229], v200, s[100:101] offset:512
	v_mfma_f32_32x32x16_bf16 a[0:15], v[48:51], v[28:31], a[0:15]
	s_waitcnt vmcnt(11)
	ds_write_b128 v186, v[222:225] offset:32256
	ds_read_b128 v[12:15], v189 offset:96
	ds_read_b128 v[24:27], v187 offset:36960
	ds_read_b128 v[16:19], v189 offset:4704
	ds_read_b128 v[28:31], v187 offset:41568
	ds_read_b128 v[20:23], v189 offset:9312
	ds_read_b128 v[48:51], v188 offset:96
	s_waitcnt lgkmcnt(14)
	v_mfma_f32_32x32x16_bf16 a[32:47], v[52:55], v[4:7], a[32:47]
	global_load_dwordx4 v[222:225], v199, s[100:101] offset:512
	s_waitcnt lgkmcnt(12)
	v_mfma_f32_32x32x16_bf16 a[48:63], v[52:55], v[8:11], a[48:63]
	s_waitcnt vmcnt(11)
	ds_write_b128 v186, v[218:221] offset:36864
	v_mfma_f32_32x32x16_bf16 a[64:79], v[56:59], v[4:7], a[64:79]
	global_load_dwordx4 v[218:221], v198, s[98:99] offset:256
	v_mfma_f32_32x32x16_bf16 a[96:111], v[56:59], v[8:11], a[96:111]
	s_waitcnt vmcnt(11)
	ds_write_b128 v186, v[214:217] offset:41472
	s_waitcnt lgkmcnt(13)
	v_mfma_f32_32x32x16_bf16 a[80:95], v[60:63], v[4:7], a[80:95]
	global_load_dwordx4 v[214:217], v197, s[98:99] offset:256
	v_mfma_f32_32x32x16_bf16 a[112:127], v[60:63], v[8:11], a[112:127]
	s_waitcnt vmcnt(11)
	ds_write_b128 v186, v[210:213] offset:46080
	s_waitcnt lgkmcnt(13)
	v_mfma_f32_32x32x16_bf16 a[16:31], v[64:67], v[4:7], a[16:31]
	global_load_dwordx4 v[210:213], v196, s[98:99] offset:256
	v_mfma_f32_32x32x16_bf16 a[0:15], v[64:67], v[8:11], a[0:15]
	s_waitcnt vmcnt(11)
	ds_write_b128 v186, v[206:209] offset:50688
	s_waitcnt lgkmcnt(0)
	v_mfma_f32_32x32x16_bf16 a[32:47], v[12:15], v[24:27], a[32:47]
	global_load_dwordx4 v[206:209], v195, s[98:99] offset:256
	s_add_u32 s100, s100, 0x80
	s_addc_u32 s101, s101, 0
	s_add_u32 s98, s98, 0x80
	s_addc_u32 s99, s99, 0
	v_mfma_f32_32x32x16_bf16 a[48:63], v[12:15], v[28:31], a[48:63]
	v_mfma_f32_32x32x16_bf16 a[64:79], v[16:19], v[24:27], a[64:79]
	v_mfma_f32_32x32x16_bf16 a[96:111], v[16:19], v[28:31], a[96:111]
	s_barrier
	v_add_u32_e32 v189, s7, v192
	v_add_u32_e32 v188, s7, v191
	v_add_u32_e32 v187, s7, v190
	ds_read_b128 v[52:55], v189
	ds_read_b128 v[4:7], v187 offset:36864
	ds_read_b128 v[56:59], v189 offset:4608
	ds_read_b128 v[8:11], v187 offset:41472
	ds_read_b128 v[60:63], v189 offset:9216
	ds_read_b128 v[64:67], v188
	v_mfma_f32_32x32x16_bf16 a[80:95], v[20:23], v[24:27], a[80:95]
	v_mfma_f32_32x32x16_bf16 a[112:127], v[20:23], v[28:31], a[112:127]
	v_mfma_f32_32x32x16_bf16 a[16:31], v[48:51], v[24:27], a[16:31]
	v_mfma_f32_32x32x16_bf16 a[0:15], v[48:51], v[28:31], a[0:15]
	s_add_u32 s2, s2, 0x80
	s_addc_u32 s3, s3, 0
	s_cmpk_lg_i32 s2, 0x700
	s_cbranch_scc1 xg5_varB_1

.LBB0_778:
	s_and_b32 s52, s44, 1
	s_mul_i32 s53, s52, 0xd800
	s_xor_b32 s52, s52, 1
	s_mul_i32 s52, s52, 0xd800
	s_add_i32 s44, s44, 1
	v_add_u32_e32 v186, s52, v45
	ds_read_b128 v[68:71], v189 offset:32
	ds_read_b128 v[80:83], v187 offset:36896
	ds_read_b128 v[72:75], v189 offset:4640
	ds_read_b128 v[84:87], v187 offset:41504
	ds_read_b128 v[76:79], v189 offset:9248
	ds_read_b128 v[104:107], v188 offset:32
	s_waitcnt lgkmcnt(10)
	v_mfma_f32_32x32x16_bf16 a[32:47], v[108:111], v[14:17], a[32:47]
	s_waitcnt vmcnt(11)
	ds_write_b128 v186, v[250:253]
	s_waitcnt lgkmcnt(9)
	v_mfma_f32_32x32x16_bf16 a[48:63], v[108:111], v[64:67], a[48:63]
	global_load_dwordx4 v[250:253], v254, s[100:101] offset:512
	v_mfma_f32_32x32x16_bf16 a[64:79], v[112:115], v[14:17], a[64:79]
	s_waitcnt vmcnt(11)
	ds_write_b128 v186, v[246:249] offset:4608
	v_mfma_f32_32x32x16_bf16 a[96:111], v[112:115], v[64:67], a[96:111]
	global_load_dwordx4 v[246:249], v205, s[100:101] offset:512
	s_waitcnt lgkmcnt(9)
	v_mfma_f32_32x32x16_bf16 a[80:95], v[116:119], v[14:17], a[80:95]
	s_waitcnt vmcnt(11)
	ds_write_b128 v186, v[242:245] offset:9216
	v_mfma_f32_32x32x16_bf16 a[112:127], v[116:119], v[64:67], a[112:127]
	global_load_dwordx4 v[242:245], v204, s[100:101] offset:512
	s_waitcnt lgkmcnt(9)
	v_mfma_f32_32x32x16_bf16 a[16:31], v[120:123], v[14:17], a[16:31]
	s_waitcnt vmcnt(11)
	ds_write_b128 v186, v[238:241] offset:13824
	v_mfma_f32_32x32x16_bf16 a[0:15], v[120:123], v[64:67], a[0:15]
	global_load_dwordx4 v[238:241], v203, s[100:101] offset:512
	ds_read_b128 v[108:111], v189 offset:64
	ds_read_b128 v[14:17], v187 offset:36928
	ds_read_b128 v[112:115], v189 offset:4672
	ds_read_b128 v[64:67], v187 offset:41536
	ds_read_b128 v[116:119], v189 offset:9280
	ds_read_b128 v[120:123], v188 offset:64
	s_waitcnt lgkmcnt(14)
	v_mfma_f32_32x32x16_bf16 a[32:47], v[68:71], v[80:83], a[32:47]
	s_waitcnt vmcnt(11)
	ds_write_b128 v186, v[234:237] offset:18432
	s_waitcnt lgkmcnt(13)
	v_mfma_f32_32x32x16_bf16 a[48:63], v[68:71], v[84:87], a[48:63]
	global_load_dwordx4 v[234:237], v202, s[100:101] offset:512
	v_mfma_f32_32x32x16_bf16 a[64:79], v[72:75], v[80:83], a[64:79]
	s_waitcnt vmcnt(11)
	ds_write_b128 v186, v[230:233] offset:23040
	v_mfma_f32_32x32x16_bf16 a[96:111], v[72:75], v[84:87], a[96:111]
	global_load_dwordx4 v[230:233], v201, s[100:101] offset:512
	s_waitcnt lgkmcnt(13)
	v_mfma_f32_32x32x16_bf16 a[80:95], v[76:79], v[80:83], a[80:95]
	s_waitcnt vmcnt(11)
	ds_write_b128 v186, v[226:229] offset:27648
	v_mfma_f32_32x32x16_bf16 a[112:127], v[76:79], v[84:87], a[112:127]
	global_load_dwordx4 v[226:229], v200, s[100:101] offset:512
	s_waitcnt lgkmcnt(13)
	v_mfma_f32_32x32x16_bf16 a[16:31], v[104:107], v[80:83], a[16:31]
	s_waitcnt vmcnt(11)
	ds_write_b128 v186, v[222:225] offset:32256
	v_mfma_f32_32x32x16_bf16 a[0:15], v[104:107], v[84:87], a[0:15]
	global_load_dwordx4 v[222:225], v199, s[100:101] offset:512
	ds_read_b128 v[68:71], v189 offset:96
	ds_read_b128 v[80:83], v187 offset:36960
	ds_read_b128 v[72:75], v189 offset:4704
	ds_read_b128 v[84:87], v187 offset:41568
	ds_read_b128 v[76:79], v189 offset:9312
	ds_read_b128 v[104:107], v188 offset:96
	s_waitcnt lgkmcnt(14)
	v_mfma_f32_32x32x16_bf16 a[32:47], v[108:111], v[14:17], a[32:47]
	s_waitcnt vmcnt(11)
	ds_write_b128 v186, v[218:221] offset:36864
	s_waitcnt lgkmcnt(13)
	v_mfma_f32_32x32x16_bf16 a[48:63], v[108:111], v[64:67], a[48:63]
	global_load_dwordx4 v[218:221], v198, s[98:99] offset:256
	v_mfma_f32_32x32x16_bf16 a[64:79], v[112:115], v[14:17], a[64:79]
	s_waitcnt vmcnt(11)
	ds_write_b128 v186, v[214:217] offset:41472
	v_mfma_f32_32x32x16_bf16 a[96:111], v[112:115], v[64:67], a[96:111]
	global_load_dwordx4 v[214:217], v197, s[98:99] offset:256
	s_waitcnt lgkmcnt(13)
	v_mfma_f32_32x32x16_bf16 a[80:95], v[116:119], v[14:17], a[80:95]
	s_waitcnt vmcnt(11)
	ds_write_b128 v186, v[210:213] offset:46080
	v_mfma_f32_32x32x16_bf16 a[112:127], v[116:119], v[64:67], a[112:127]
	global_load_dwordx4 v[210:213], v196, s[98:99] offset:256
	s_waitcnt lgkmcnt(13)
	v_mfma_f32_32x32x16_bf16 a[16:31], v[120:123], v[14:17], a[16:31]
	s_waitcnt vmcnt(11)
	ds_write_b128 v186, v[206:209] offset:50688
	v_mfma_f32_32x32x16_bf16 a[0:15], v[120:123], v[64:67], a[0:15]
	global_load_dwordx4 v[206:209], v195, s[98:99] offset:256
	s_add_u32 s100, s100, 0x80
	s_addc_u32 s101, s101, 0
	s_add_u32 s98, s98, 0x80
	s_addc_u32 s99, s99, 0
	s_waitcnt lgkmcnt(0)
	v_mfma_f32_32x32x16_bf16 a[32:47], v[68:71], v[80:83], a[32:47]
	v_mfma_f32_32x32x16_bf16 a[48:63], v[68:71], v[84:87], a[48:63]
	v_mfma_f32_32x32x16_bf16 a[64:79], v[72:75], v[80:83], a[64:79]
	v_mfma_f32_32x32x16_bf16 a[96:111], v[72:75], v[84:87], a[96:111]
	s_barrier
	v_add_u32_e32 v189, s52, v192
	v_add_u32_e32 v188, s52, v191
	v_add_u32_e32 v187, s52, v190
	ds_read_b128 v[108:111], v189
	ds_read_b128 v[14:17], v187 offset:36864
	ds_read_b128 v[112:115], v189 offset:4608
	ds_read_b128 v[64:67], v187 offset:41472
	ds_read_b128 v[116:119], v189 offset:9216
	ds_read_b128 v[120:123], v188
	v_mfma_f32_32x32x16_bf16 a[80:95], v[76:79], v[80:83], a[80:95]
	v_mfma_f32_32x32x16_bf16 a[112:127], v[76:79], v[84:87], a[112:127]
	v_mfma_f32_32x32x16_bf16 a[16:31], v[104:107], v[80:83], a[16:31]
	v_mfma_f32_32x32x16_bf16 a[0:15], v[104:107], v[84:87], a[0:15]
	s_add_u32 s46, s46, 0x80
	s_addc_u32 s47, s47, 0
	s_cmpk_lg_i32 s46, 0x700
	s_cbranch_scc1 .LBB0_778
	s_branch xg5_tail_2
xg5_varB_2:
	s_and_b32 s52, s44, 1
	s_mul_i32 s53, s52, 0xd800
	s_xor_b32 s52, s52, 1
	s_mul_i32 s52, s52, 0xd800
	s_add_i32 s44, s44, 1
	v_add_u32_e32 v186, s52, v45
	ds_read_b128 v[68:71], v189 offset:32
	ds_read_b128 v[80:83], v187 offset:36896
	ds_read_b128 v[72:75], v189 offset:4640
	ds_read_b128 v[84:87], v187 offset:41504
	ds_read_b128 v[76:79], v189 offset:9248
	ds_read_b128 v[104:107], v188 offset:32
	s_waitcnt lgkmcnt(10)
	v_mfma_f32_32x32x16_bf16 a[32:47], v[108:111], v[14:17], a[32:47]
	s_waitcnt lgkmcnt(8)
	v_mfma_f32_32x32x16_bf16 a[48:63], v[108:111], v[64:67], a[48:63]
	s_waitcnt vmcnt(11)
	ds_write_b128 v186, v[250:253]
	v_mfma_f32_32x32x16_bf16 a[64:79], v[112:115], v[14:17], a[64:79]
	global_load_dwordx4 v[250:253], v254, s[100:101] offset:512
	v_mfma_f32_32x32x16_bf16 a[96:111], v[112:115], v[64:67], a[96:111]
	s_waitcnt vmcnt(11)
	ds_write_b128 v186, v[246:249] offset:4608
	s_waitcnt lgkmcnt(9)
	v_mfma_f32_32x32x16_bf16 a[80:95], v[116:119], v[14:17], a[80:95]
	global_load_dwordx4 v[246:249], v205, s[100:101] offset:512
	v_mfma_f32_32x32x16_bf16 a[112:127], v[116:119], v[64:67], a[112:127]
	s_waitcnt vmcnt(11)
	ds_write_b128 v186, v[242:245] offset:9216
	s_waitcnt lgkmcnt(9)
	v_mfma_f32_32x32x16_bf16 a[16:31], v[120:123], v[14:17], a[16:31]
	global_load_dwordx4 v[242:245], v204, s[100:101] offset:512
	v_mfma_f32_32x32x16_bf16 a[0:15], v[120:123], v[64:67], a[0:15]
	s_waitcnt vmcnt(11)
	ds_write_b128 v186, v[238:241] offset:13824
	ds_read_b128 v[108:111], v189 offset:64
	ds_read_b128 v[14:17], v187 offset:36928
	ds_read_b128 v[112:115], v189 offset:4672
	ds_read_b128 v[64:67], v187 offset:41536
	ds_read_b128 v[116:119], v189 offset:9280
	ds_read_b128 v[120:123], v188 offset:64
	s_waitcnt lgkmcnt(14)
	v_mfma_f32_32x32x16_bf16 a[32:47], v[68:71], v[80:83], a[32:47]
	global_load_dwordx4 v[238:241], v203, s[100:101] offset:512
	s_waitcnt lgkmcnt(12)
	v_mfma_f32_32x32x16_bf16 a[48:63], v[68:71], v[84:87], a[48:63]
	s_waitcnt vmcnt(11)
	ds_write_b128 v186, v[234:237] offset:18432
	v_mfma_f32_32x32x16_bf16 a[64:79], v[72:75], v[80:83], a[64:79]
	global_load_dwordx4 v[234:237], v202, s[100:101] offset:512
	v_mfma_f32_32x32x16_bf16 a[96:111], v[72:75], v[84:87], a[96:111]
	s_waitcnt vmcnt(11)
	ds_write_b128 v186, v[230:233] offset:23040
	s_waitcnt lgkmcnt(13)
	v_mfma_f32_32x32x16_bf16 a[80:95], v[76:79], v[80:83], a[80:95]
	global_load_dwordx4 v[230:233], v201, s[100:101] offset:512
	v_mfma_f32_32x32x16_bf16 a[112:127], v[76:79], v[84:87], a[112:127]
	s_waitcnt vmcnt(11)
	ds_write_b128 v186, v[226:229] offset:27648
	s_waitcnt lgkmcnt(13)
	v_mfma_f32_32x32x16_bf16 a[16:31], v[104:107], v[80:83], a[16:31]
	global_load_dwordx4 v[226:229], v200, s[100:101] offset:512
	v_mfma_f32_32x32x16_bf16 a[0:15], v[104:107], v[84:87], a[0:15]
	s_waitcnt vmcnt(11)
	ds_write_b128 v186, v[222:225] offset:32256
	ds_read_b128 v[68:71], v189 offset:96
	ds_read_b128 v[80:83], v187 offset:36960
	ds_read_b128 v[72:75], v189 offset:4704
	ds_read_b128 v[84:87], v187 offset:41568
	ds_read_b128 v[76:79], v189 offset:9312
	ds_read_b128 v[104:107], v188 offset:96
	s_waitcnt lgkmcnt(14)
	v_mfma_f32_32x32x16_bf16 a[32:47], v[108:111], v[14:17], a[32:47]
	global_load_dwordx4 v[222:225], v199, s[100:101] offset:512
	s_waitcnt lgkmcnt(12)
	v_mfma_f32_32x32x16_bf16 a[48:63], v[108:111], v[64:67], a[48:63]
	s_waitcnt vmcnt(11)
	ds_write_b128 v186, v[218:221] offset:36864
	v_mfma_f32_32x32x16_bf16 a[64:79], v[112:115], v[14:17], a[64:79]
	global_load_dwordx4 v[218:221], v198, s[98:99] offset:256
	v_mfma_f32_32x32x16_bf16 a[96:111], v[112:115], v[64:67], a[96:111]
	s_waitcnt vmcnt(11)
	ds_write_b128 v186, v[214:217] offset:41472
	s_waitcnt lgkmcnt(13)
	v_mfma_f32_32x32x16_bf16 a[80:95], v[116:119], v[14:17], a[80:95]
	global_load_dwordx4 v[214:217], v197, s[98:99] offset:256
	v_mfma_f32_32x32x16_bf16 a[112:127], v[116:119], v[64:67], a[112:127]
	s_waitcnt vmcnt(11)
	ds_write_b128 v186, v[210:213] offset:46080
	s_waitcnt lgkmcnt(13)
	v_mfma_f32_32x32x16_bf16 a[16:31], v[120:123], v[14:17], a[16:31]
	global_load_dwordx4 v[210:213], v196, s[98:99] offset:256
	v_mfma_f32_32x32x16_bf16 a[0:15], v[120:123], v[64:67], a[0:15]
	s_waitcnt vmcnt(11)
	ds_write_b128 v186, v[206:209] offset:50688
	s_waitcnt lgkmcnt(0)
	v_mfma_f32_32x32x16_bf16 a[32:47], v[68:71], v[80:83], a[32:47]
	global_load_dwordx4 v[206:209], v195, s[98:99] offset:256
	s_add_u32 s100, s100, 0x80
	s_addc_u32 s101, s101, 0
	s_add_u32 s98, s98, 0x80
	s_addc_u32 s99, s99, 0
	v_mfma_f32_32x32x16_bf16 a[48:63], v[68:71], v[84:87], a[48:63]
	v_mfma_f32_32x32x16_bf16 a[64:79], v[72:75], v[80:83], a[64:79]
	v_mfma_f32_32x32x16_bf16 a[96:111], v[72:75], v[84:87], a[96:111]
	s_barrier
	v_add_u32_e32 v189, s52, v192
	v_add_u32_e32 v188, s52, v191
	v_add_u32_e32 v187, s52, v190
	ds_read_b128 v[108:111], v189
	ds_read_b128 v[14:17], v187 offset:36864
	ds_read_b128 v[112:115], v189 offset:4608
	ds_read_b128 v[64:67], v187 offset:41472
	ds_read_b128 v[116:119], v189 offset:9216
	ds_read_b128 v[120:123], v188
	v_mfma_f32_32x32x16_bf16 a[80:95], v[76:79], v[80:83], a[80:95]
	v_mfma_f32_32x32x16_bf16 a[112:127], v[76:79], v[84:87], a[112:127]
	v_mfma_f32_32x32x16_bf16 a[16:31], v[104:107], v[80:83], a[16:31]
	v_mfma_f32_32x32x16_bf16 a[0:15], v[104:107], v[84:87], a[0:15]
	s_add_u32 s46, s46, 0x80
	s_addc_u32 s47, s47, 0
	s_cmpk_lg_i32 s46, 0x700
	s_cbranch_scc1 xg5_varB_2

.LBB0_977:
	s_and_b32 s9, s8, 1
	s_mul_i32 s12, s9, 0xd800
	s_xor_b32 s9, s9, 1
	s_mul_i32 s9, s9, 0xd800
	s_add_i32 s8, s8, 1
	v_add_u32_e32 v186, s9, v131
	ds_read_b128 v[12:15], v189 offset:32
	ds_read_b128 v[24:27], v187 offset:36896
	ds_read_b128 v[16:19], v189 offset:4640
	ds_read_b128 v[28:31], v187 offset:41504
	ds_read_b128 v[20:23], v189 offset:9248
	ds_read_b128 v[74:77], v188 offset:32
	s_waitcnt lgkmcnt(10)
	v_mfma_f32_32x32x16_bf16 a[32:47], v[78:81], v[4:7], a[32:47]
	s_waitcnt vmcnt(11)
	ds_write_b128 v186, v[250:253]
	s_waitcnt lgkmcnt(9)
	v_mfma_f32_32x32x16_bf16 a[48:63], v[78:81], v[8:11], a[48:63]
	global_load_dwordx4 v[250:253], v254, s[100:101] offset:512
	v_mfma_f32_32x32x16_bf16 a[64:79], v[82:85], v[4:7], a[64:79]
	s_waitcnt vmcnt(11)
	ds_write_b128 v186, v[246:249] offset:4608
	v_mfma_f32_32x32x16_bf16 a[96:111], v[82:85], v[8:11], a[96:111]
	global_load_dwordx4 v[246:249], v205, s[100:101] offset:512
	s_waitcnt lgkmcnt(9)
	v_mfma_f32_32x32x16_bf16 a[80:95], v[86:89], v[4:7], a[80:95]
	s_waitcnt vmcnt(11)
	ds_write_b128 v186, v[242:245] offset:9216
	v_mfma_f32_32x32x16_bf16 a[112:127], v[86:89], v[8:11], a[112:127]
	global_load_dwordx4 v[242:245], v204, s[100:101] offset:512
	s_waitcnt lgkmcnt(9)
	v_mfma_f32_32x32x16_bf16 a[16:31], v[90:93], v[4:7], a[16:31]
	s_waitcnt vmcnt(11)
	ds_write_b128 v186, v[238:241] offset:13824
	v_mfma_f32_32x32x16_bf16 a[0:15], v[90:93], v[8:11], a[0:15]
	global_load_dwordx4 v[238:241], v203, s[100:101] offset:512
	ds_read_b128 v[78:81], v189 offset:64
	ds_read_b128 v[4:7], v187 offset:36928
	ds_read_b128 v[82:85], v189 offset:4672
	ds_read_b128 v[8:11], v187 offset:41536
	ds_read_b128 v[86:89], v189 offset:9280
	ds_read_b128 v[90:93], v188 offset:64
	s_waitcnt lgkmcnt(14)
	v_mfma_f32_32x32x16_bf16 a[32:47], v[12:15], v[24:27], a[32:47]
	s_waitcnt vmcnt(11)
	ds_write_b128 v186, v[234:237] offset:18432
	s_waitcnt lgkmcnt(13)
	v_mfma_f32_32x32x16_bf16 a[48:63], v[12:15], v[28:31], a[48:63]
	global_load_dwordx4 v[234:237], v202, s[100:101] offset:512
	v_mfma_f32_32x32x16_bf16 a[64:79], v[16:19], v[24:27], a[64:79]
	s_waitcnt vmcnt(11)
	ds_write_b128 v186, v[230:233] offset:23040
	v_mfma_f32_32x32x16_bf16 a[96:111], v[16:19], v[28:31], a[96:111]
	global_load_dwordx4 v[230:233], v201, s[100:101] offset:512
	s_waitcnt lgkmcnt(13)
	v_mfma_f32_32x32x16_bf16 a[80:95], v[20:23], v[24:27], a[80:95]
	s_waitcnt vmcnt(11)
	ds_write_b128 v186, v[226:229] offset:27648
	v_mfma_f32_32x32x16_bf16 a[112:127], v[20:23], v[28:31], a[112:127]
	global_load_dwordx4 v[226:229], v200, s[100:101] offset:512
	s_waitcnt lgkmcnt(13)
	v_mfma_f32_32x32x16_bf16 a[16:31], v[74:77], v[24:27], a[16:31]
	s_waitcnt vmcnt(11)
	ds_write_b128 v186, v[222:225] offset:32256
	v_mfma_f32_32x32x16_bf16 a[0:15], v[74:77], v[28:31], a[0:15]
	global_load_dwordx4 v[222:225], v199, s[100:101] offset:512
	ds_read_b128 v[12:15], v189 offset:96
	ds_read_b128 v[24:27], v187 offset:36960
	ds_read_b128 v[16:19], v189 offset:4704
	ds_read_b128 v[28:31], v187 offset:41568
	ds_read_b128 v[20:23], v189 offset:9312
	ds_read_b128 v[74:77], v188 offset:96
	s_waitcnt lgkmcnt(14)
	v_mfma_f32_32x32x16_bf16 a[32:47], v[78:81], v[4:7], a[32:47]
	s_waitcnt vmcnt(11)
	ds_write_b128 v186, v[218:221] offset:36864
	s_waitcnt lgkmcnt(13)
	v_mfma_f32_32x32x16_bf16 a[48:63], v[78:81], v[8:11], a[48:63]
	global_load_dwordx4 v[218:221], v198, s[98:99] offset:256
	v_mfma_f32_32x32x16_bf16 a[64:79], v[82:85], v[4:7], a[64:79]
	s_waitcnt vmcnt(11)
	ds_write_b128 v186, v[214:217] offset:41472
	v_mfma_f32_32x32x16_bf16 a[96:111], v[82:85], v[8:11], a[96:111]
	global_load_dwordx4 v[214:217], v197, s[98:99] offset:256
	s_waitcnt lgkmcnt(13)
	v_mfma_f32_32x32x16_bf16 a[80:95], v[86:89], v[4:7], a[80:95]
	s_waitcnt vmcnt(11)
	ds_write_b128 v186, v[210:213] offset:46080
	v_mfma_f32_32x32x16_bf16 a[112:127], v[86:89], v[8:11], a[112:127]
	global_load_dwordx4 v[210:213], v196, s[98:99] offset:256
	s_waitcnt lgkmcnt(13)
	v_mfma_f32_32x32x16_bf16 a[16:31], v[90:93], v[4:7], a[16:31]
	s_waitcnt vmcnt(11)
	ds_write_b128 v186, v[206:209] offset:50688
	v_mfma_f32_32x32x16_bf16 a[0:15], v[90:93], v[8:11], a[0:15]
	global_load_dwordx4 v[206:209], v195, s[98:99] offset:256
	s_add_u32 s100, s100, 0x80
	s_addc_u32 s101, s101, 0
	s_add_u32 s98, s98, 0x80
	s_addc_u32 s99, s99, 0
	s_waitcnt lgkmcnt(0)
	v_mfma_f32_32x32x16_bf16 a[32:47], v[12:15], v[24:27], a[32:47]
	v_mfma_f32_32x32x16_bf16 a[48:63], v[12:15], v[28:31], a[48:63]
	v_mfma_f32_32x32x16_bf16 a[64:79], v[16:19], v[24:27], a[64:79]
	v_mfma_f32_32x32x16_bf16 a[96:111], v[16:19], v[28:31], a[96:111]
	s_barrier
	v_add_u32_e32 v189, s9, v192
	v_add_u32_e32 v188, s9, v191
	v_add_u32_e32 v187, s9, v190
	ds_read_b128 v[78:81], v189
	ds_read_b128 v[4:7], v187 offset:36864
	ds_read_b128 v[82:85], v189 offset:4608
	ds_read_b128 v[8:11], v187 offset:41472
	ds_read_b128 v[86:89], v189 offset:9216
	ds_read_b128 v[90:93], v188
	v_mfma_f32_32x32x16_bf16 a[80:95], v[20:23], v[24:27], a[80:95]
	v_mfma_f32_32x32x16_bf16 a[112:127], v[20:23], v[28:31], a[112:127]
	v_mfma_f32_32x32x16_bf16 a[16:31], v[74:77], v[24:27], a[16:31]
	v_mfma_f32_32x32x16_bf16 a[0:15], v[74:77], v[28:31], a[0:15]
	s_add_u32 s6, s6, 0x80
	s_addc_u32 s7, s7, 0
	s_cmpk_lg_i32 s6, 0x700
	s_cbranch_scc1 .LBB0_977
	s_branch xg5_tail_3
xg5_varB_3:
	s_and_b32 s9, s8, 1
	s_mul_i32 s12, s9, 0xd800
	s_xor_b32 s9, s9, 1
	s_mul_i32 s9, s9, 0xd800
	s_add_i32 s8, s8, 1
	v_add_u32_e32 v186, s9, v131
	ds_read_b128 v[12:15], v189 offset:32
	ds_read_b128 v[24:27], v187 offset:36896
	ds_read_b128 v[16:19], v189 offset:4640
	ds_read_b128 v[28:31], v187 offset:41504
	ds_read_b128 v[20:23], v189 offset:9248
	ds_read_b128 v[74:77], v188 offset:32
	s_waitcnt lgkmcnt(10)
	v_mfma_f32_32x32x16_bf16 a[32:47], v[78:81], v[4:7], a[32:47]
	s_waitcnt lgkmcnt(8)
	v_mfma_f32_32x32x16_bf16 a[48:63], v[78:81], v[8:11], a[48:63]
	s_waitcnt vmcnt(11)
	ds_write_b128 v186, v[250:253]
	v_mfma_f32_32x32x16_bf16 a[64:79], v[82:85], v[4:7], a[64:79]
	global_load_dwordx4 v[250:253], v254, s[100:101] offset:512
	v_mfma_f32_32x32x16_bf16 a[96:111], v[82:85], v[8:11], a[96:111]
	s_waitcnt vmcnt(11)
	ds_write_b128 v186, v[246:249] offset:4608
	s_waitcnt lgkmcnt(9)
	v_mfma_f32_32x32x16_bf16 a[80:95], v[86:89], v[4:7], a[80:95]
	global_load_dwordx4 v[246:249], v205, s[100:101] offset:512
	v_mfma_f32_32x32x16_bf16 a[112:127], v[86:89], v[8:11], a[112:127]
	s_waitcnt vmcnt(11)
	ds_write_b128 v186, v[242:245] offset:9216
	s_waitcnt lgkmcnt(9)
	v_mfma_f32_32x32x16_bf16 a[16:31], v[90:93], v[4:7], a[16:31]
	global_load_dwordx4 v[242:245], v204, s[100:101] offset:512
	v_mfma_f32_32x32x16_bf16 a[0:15], v[90:93], v[8:11], a[0:15]
	s_waitcnt vmcnt(11)
	ds_write_b128 v186, v[238:241] offset:13824
	ds_read_b128 v[78:81], v189 offset:64
	ds_read_b128 v[4:7], v187 offset:36928
	ds_read_b128 v[82:85], v189 offset:4672
	ds_read_b128 v[8:11], v187 offset:41536
	ds_read_b128 v[86:89], v189 offset:9280
	ds_read_b128 v[90:93], v188 offset:64
	s_waitcnt lgkmcnt(14)
	v_mfma_f32_32x32x16_bf16 a[32:47], v[12:15], v[24:27], a[32:47]
	global_load_dwordx4 v[238:241], v203, s[100:101] offset:512
	s_waitcnt lgkmcnt(12)
	v_mfma_f32_32x32x16_bf16 a[48:63], v[12:15], v[28:31], a[48:63]
	s_waitcnt vmcnt(11)
	ds_write_b128 v186, v[234:237] offset:18432
	v_mfma_f32_32x32x16_bf16 a[64:79], v[16:19], v[24:27], a[64:79]
	global_load_dwordx4 v[234:237], v202, s[100:101] offset:512
	v_mfma_f32_32x32x16_bf16 a[96:111], v[16:19], v[28:31], a[96:111]
	s_waitcnt vmcnt(11)
	ds_write_b128 v186, v[230:233] offset:23040
	s_waitcnt lgkmcnt(13)
	v_mfma_f32_32x32x16_bf16 a[80:95], v[20:23], v[24:27], a[80:95]
	global_load_dwordx4 v[230:233], v201, s[100:101] offset:512
	v_mfma_f32_32x32x16_bf16 a[112:127], v[20:23], v[28:31], a[112:127]
	s_waitcnt vmcnt(11)
	ds_write_b128 v186, v[226:229] offset:27648
	s_waitcnt lgkmcnt(13)
	v_mfma_f32_32x32x16_bf16 a[16:31], v[74:77], v[24:27], a[16:31]
	global_load_dwordx4 v[226:229], v200, s[100:101] offset:512
	v_mfma_f32_32x32x16_bf16 a[0:15], v[74:77], v[28:31], a[0:15]
	s_waitcnt vmcnt(11)
	ds_write_b128 v186, v[222:225] offset:32256
	ds_read_b128 v[12:15], v189 offset:96
	ds_read_b128 v[24:27], v187 offset:36960
	ds_read_b128 v[16:19], v189 offset:4704
	ds_read_b128 v[28:31], v187 offset:41568
	ds_read_b128 v[20:23], v189 offset:9312
	ds_read_b128 v[74:77], v188 offset:96
	s_waitcnt lgkmcnt(14)
	v_mfma_f32_32x32x16_bf16 a[32:47], v[78:81], v[4:7], a[32:47]
	global_load_dwordx4 v[222:225], v199, s[100:101] offset:512
	s_waitcnt lgkmcnt(12)
	v_mfma_f32_32x32x16_bf16 a[48:63], v[78:81], v[8:11], a[48:63]
	s_waitcnt vmcnt(11)
	ds_write_b128 v186, v[218:221] offset:36864
	v_mfma_f32_32x32x16_bf16 a[64:79], v[82:85], v[4:7], a[64:79]
	global_load_dwordx4 v[218:221], v198, s[98:99] offset:256
	v_mfma_f32_32x32x16_bf16 a[96:111], v[82:85], v[8:11], a[96:111]
	s_waitcnt vmcnt(11)
	ds_write_b128 v186, v[214:217] offset:41472
	s_waitcnt lgkmcnt(13)
	v_mfma_f32_32x32x16_bf16 a[80:95], v[86:89], v[4:7], a[80:95]
	global_load_dwordx4 v[214:217], v197, s[98:99] offset:256
	v_mfma_f32_32x32x16_bf16 a[112:127], v[86:89], v[8:11], a[112:127]
	s_waitcnt vmcnt(11)
	ds_write_b128 v186, v[210:213] offset:46080
	s_waitcnt lgkmcnt(13)
	v_mfma_f32_32x32x16_bf16 a[16:31], v[90:93], v[4:7], a[16:31]
	global_load_dwordx4 v[210:213], v196, s[98:99] offset:256
	v_mfma_f32_32x32x16_bf16 a[0:15], v[90:93], v[8:11], a[0:15]
	s_waitcnt vmcnt(11)
	ds_write_b128 v186, v[206:209] offset:50688
	s_waitcnt lgkmcnt(0)
	v_mfma_f32_32x32x16_bf16 a[32:47], v[12:15], v[24:27], a[32:47]
	global_load_dwordx4 v[206:209], v195, s[98:99] offset:256
	s_add_u32 s100, s100, 0x80
	s_addc_u32 s101, s101, 0
	s_add_u32 s98, s98, 0x80
	s_addc_u32 s99, s99, 0
	v_mfma_f32_32x32x16_bf16 a[48:63], v[12:15], v[28:31], a[48:63]
	v_mfma_f32_32x32x16_bf16 a[64:79], v[16:19], v[24:27], a[64:79]
	v_mfma_f32_32x32x16_bf16 a[96:111], v[16:19], v[28:31], a[96:111]
	s_barrier
	v_add_u32_e32 v189, s9, v192
	v_add_u32_e32 v188, s9, v191
	v_add_u32_e32 v187, s9, v190
	ds_read_b128 v[78:81], v189
	ds_read_b128 v[4:7], v187 offset:36864
	ds_read_b128 v[82:85], v189 offset:4608
	ds_read_b128 v[8:11], v187 offset:41472
	ds_read_b128 v[86:89], v189 offset:9216
	ds_read_b128 v[90:93], v188
	v_mfma_f32_32x32x16_bf16 a[80:95], v[20:23], v[24:27], a[80:95]
	v_mfma_f32_32x32x16_bf16 a[112:127], v[20:23], v[28:31], a[112:127]
	v_mfma_f32_32x32x16_bf16 a[16:31], v[74:77], v[24:27], a[16:31]
	v_mfma_f32_32x32x16_bf16 a[0:15], v[74:77], v[28:31], a[0:15]
	s_add_u32 s6, s6, 0x80
	s_addc_u32 s7, s7, 0
	s_cmpk_lg_i32 s6, 0x700
	s_cbranch_scc1 xg5_varB_3

.LBB0_1265:
	s_and_b32 s50, s42, 1
	s_mul_i32 s51, s50, 0xd800
	s_xor_b32 s50, s50, 1
	s_mul_i32 s50, s50, 0xd800
	s_add_i32 s42, s42, 1
	v_add_u32_e32 v186, s50, v45
	ds_read_b128 v[68:71], v189 offset:32
	ds_read_b128 v[80:83], v187 offset:36896
	ds_read_b128 v[72:75], v189 offset:4640
	ds_read_b128 v[84:87], v187 offset:41504
	ds_read_b128 v[76:79], v189 offset:9248
	ds_read_b128 v[104:107], v188 offset:32
	s_waitcnt lgkmcnt(10)
	v_mfma_f32_32x32x16_bf16 a[32:47], v[108:111], v[14:17], a[32:47]
	s_waitcnt vmcnt(11)
	ds_write_b128 v186, v[250:253]
	s_waitcnt lgkmcnt(9)
	v_mfma_f32_32x32x16_bf16 a[48:63], v[108:111], v[64:67], a[48:63]
	global_load_dwordx4 v[250:253], v254, s[100:101] offset:512
	v_mfma_f32_32x32x16_bf16 a[64:79], v[112:115], v[14:17], a[64:79]
	s_waitcnt vmcnt(11)
	ds_write_b128 v186, v[246:249] offset:4608
	v_mfma_f32_32x32x16_bf16 a[96:111], v[112:115], v[64:67], a[96:111]
	global_load_dwordx4 v[246:249], v205, s[100:101] offset:512
	s_waitcnt lgkmcnt(9)
	v_mfma_f32_32x32x16_bf16 a[80:95], v[116:119], v[14:17], a[80:95]
	s_waitcnt vmcnt(11)
	ds_write_b128 v186, v[242:245] offset:9216
	v_mfma_f32_32x32x16_bf16 a[112:127], v[116:119], v[64:67], a[112:127]
	global_load_dwordx4 v[242:245], v204, s[100:101] offset:512
	s_waitcnt lgkmcnt(9)
	v_mfma_f32_32x32x16_bf16 a[16:31], v[120:123], v[14:17], a[16:31]
	s_waitcnt vmcnt(11)
	ds_write_b128 v186, v[238:241] offset:13824
	v_mfma_f32_32x32x16_bf16 a[0:15], v[120:123], v[64:67], a[0:15]
	global_load_dwordx4 v[238:241], v203, s[100:101] offset:512
	ds_read_b128 v[108:111], v189 offset:64
	ds_read_b128 v[14:17], v187 offset:36928
	ds_read_b128 v[112:115], v189 offset:4672
	ds_read_b128 v[64:67], v187 offset:41536
	ds_read_b128 v[116:119], v189 offset:9280
	ds_read_b128 v[120:123], v188 offset:64
	s_waitcnt lgkmcnt(14)
	v_mfma_f32_32x32x16_bf16 a[32:47], v[68:71], v[80:83], a[32:47]
	s_waitcnt vmcnt(11)
	ds_write_b128 v186, v[234:237] offset:18432
	s_waitcnt lgkmcnt(13)
	v_mfma_f32_32x32x16_bf16 a[48:63], v[68:71], v[84:87], a[48:63]
	global_load_dwordx4 v[234:237], v202, s[100:101] offset:512
	v_mfma_f32_32x32x16_bf16 a[64:79], v[72:75], v[80:83], a[64:79]
	s_waitcnt vmcnt(11)
	ds_write_b128 v186, v[230:233] offset:23040
	v_mfma_f32_32x32x16_bf16 a[96:111], v[72:75], v[84:87], a[96:111]
	global_load_dwordx4 v[230:233], v201, s[100:101] offset:512
	s_waitcnt lgkmcnt(13)
	v_mfma_f32_32x32x16_bf16 a[80:95], v[76:79], v[80:83], a[80:95]
	s_waitcnt vmcnt(11)
	ds_write_b128 v186, v[226:229] offset:27648
	v_mfma_f32_32x32x16_bf16 a[112:127], v[76:79], v[84:87], a[112:127]
	global_load_dwordx4 v[226:229], v200, s[100:101] offset:512
	s_waitcnt lgkmcnt(13)
	v_mfma_f32_32x32x16_bf16 a[16:31], v[104:107], v[80:83], a[16:31]
	s_waitcnt vmcnt(11)
	ds_write_b128 v186, v[222:225] offset:32256
	v_mfma_f32_32x32x16_bf16 a[0:15], v[104:107], v[84:87], a[0:15]
	global_load_dwordx4 v[222:225], v199, s[100:101] offset:512
	ds_read_b128 v[68:71], v189 offset:96
	ds_read_b128 v[80:83], v187 offset:36960
	ds_read_b128 v[72:75], v189 offset:4704
	ds_read_b128 v[84:87], v187 offset:41568
	ds_read_b128 v[76:79], v189 offset:9312
	ds_read_b128 v[104:107], v188 offset:96
	s_waitcnt lgkmcnt(14)
	v_mfma_f32_32x32x16_bf16 a[32:47], v[108:111], v[14:17], a[32:47]
	s_waitcnt vmcnt(11)
	ds_write_b128 v186, v[218:221] offset:36864
	s_waitcnt lgkmcnt(13)
	v_mfma_f32_32x32x16_bf16 a[48:63], v[108:111], v[64:67], a[48:63]
	global_load_dwordx4 v[218:221], v198, s[98:99] offset:256
	v_mfma_f32_32x32x16_bf16 a[64:79], v[112:115], v[14:17], a[64:79]
	s_waitcnt vmcnt(11)
	ds_write_b128 v186, v[214:217] offset:41472
	v_mfma_f32_32x32x16_bf16 a[96:111], v[112:115], v[64:67], a[96:111]
	global_load_dwordx4 v[214:217], v197, s[98:99] offset:256
	s_waitcnt lgkmcnt(13)
	v_mfma_f32_32x32x16_bf16 a[80:95], v[116:119], v[14:17], a[80:95]
	s_waitcnt vmcnt(11)
	ds_write_b128 v186, v[210:213] offset:46080
	v_mfma_f32_32x32x16_bf16 a[112:127], v[116:119], v[64:67], a[112:127]
	global_load_dwordx4 v[210:213], v196, s[98:99] offset:256
	s_waitcnt lgkmcnt(13)
	v_mfma_f32_32x32x16_bf16 a[16:31], v[120:123], v[14:17], a[16:31]
	s_waitcnt vmcnt(11)
	ds_write_b128 v186, v[206:209] offset:50688
	v_mfma_f32_32x32x16_bf16 a[0:15], v[120:123], v[64:67], a[0:15]
	global_load_dwordx4 v[206:209], v195, s[98:99] offset:256
	s_add_u32 s100, s100, 0x80
	s_addc_u32 s101, s101, 0
	s_add_u32 s98, s98, 0x80
	s_addc_u32 s99, s99, 0
	s_waitcnt lgkmcnt(0)
	v_mfma_f32_32x32x16_bf16 a[32:47], v[68:71], v[80:83], a[32:47]
	v_mfma_f32_32x32x16_bf16 a[48:63], v[68:71], v[84:87], a[48:63]
	v_mfma_f32_32x32x16_bf16 a[64:79], v[72:75], v[80:83], a[64:79]
	v_mfma_f32_32x32x16_bf16 a[96:111], v[72:75], v[84:87], a[96:111]
	s_barrier
	v_add_u32_e32 v189, s50, v192
	v_add_u32_e32 v188, s50, v191
	v_add_u32_e32 v187, s50, v190
	ds_read_b128 v[108:111], v189
	ds_read_b128 v[14:17], v187 offset:36864
	ds_read_b128 v[112:115], v189 offset:4608
	ds_read_b128 v[64:67], v187 offset:41472
	ds_read_b128 v[116:119], v189 offset:9216
	ds_read_b128 v[120:123], v188
	v_mfma_f32_32x32x16_bf16 a[80:95], v[76:79], v[80:83], a[80:95]
	v_mfma_f32_32x32x16_bf16 a[112:127], v[76:79], v[84:87], a[112:127]
	v_mfma_f32_32x32x16_bf16 a[16:31], v[104:107], v[80:83], a[16:31]
	v_mfma_f32_32x32x16_bf16 a[0:15], v[104:107], v[84:87], a[0:15]
	s_add_u32 s44, s44, 0x80
	s_addc_u32 s45, s45, 0
	s_cmpk_lg_i32 s44, 0x700
	s_cbranch_scc1 .LBB0_1265
	s_branch xg5_tail_4
xg5_varB_4:
	s_and_b32 s50, s42, 1
	s_mul_i32 s51, s50, 0xd800
	s_xor_b32 s50, s50, 1
	s_mul_i32 s50, s50, 0xd800
	s_add_i32 s42, s42, 1
	v_add_u32_e32 v186, s50, v45
	ds_read_b128 v[68:71], v189 offset:32
	ds_read_b128 v[80:83], v187 offset:36896
	ds_read_b128 v[72:75], v189 offset:4640
	ds_read_b128 v[84:87], v187 offset:41504
	ds_read_b128 v[76:79], v189 offset:9248
	ds_read_b128 v[104:107], v188 offset:32
	s_waitcnt lgkmcnt(10)
	v_mfma_f32_32x32x16_bf16 a[32:47], v[108:111], v[14:17], a[32:47]
	s_waitcnt lgkmcnt(8)
	v_mfma_f32_32x32x16_bf16 a[48:63], v[108:111], v[64:67], a[48:63]
	s_waitcnt vmcnt(11)
	ds_write_b128 v186, v[250:253]
	v_mfma_f32_32x32x16_bf16 a[64:79], v[112:115], v[14:17], a[64:79]
	global_load_dwordx4 v[250:253], v254, s[100:101] offset:512
	v_mfma_f32_32x32x16_bf16 a[96:111], v[112:115], v[64:67], a[96:111]
	s_waitcnt vmcnt(11)
	ds_write_b128 v186, v[246:249] offset:4608
	s_waitcnt lgkmcnt(9)
	v_mfma_f32_32x32x16_bf16 a[80:95], v[116:119], v[14:17], a[80:95]
	global_load_dwordx4 v[246:249], v205, s[100:101] offset:512
	v_mfma_f32_32x32x16_bf16 a[112:127], v[116:119], v[64:67], a[112:127]
	s_waitcnt vmcnt(11)
	ds_write_b128 v186, v[242:245] offset:9216
	s_waitcnt lgkmcnt(9)
	v_mfma_f32_32x32x16_bf16 a[16:31], v[120:123], v[14:17], a[16:31]
	global_load_dwordx4 v[242:245], v204, s[100:101] offset:512
	v_mfma_f32_32x32x16_bf16 a[0:15], v[120:123], v[64:67], a[0:15]
	s_waitcnt vmcnt(11)
	ds_write_b128 v186, v[238:241] offset:13824
	ds_read_b128 v[108:111], v189 offset:64
	ds_read_b128 v[14:17], v187 offset:36928
	ds_read_b128 v[112:115], v189 offset:4672
	ds_read_b128 v[64:67], v187 offset:41536
	ds_read_b128 v[116:119], v189 offset:9280
	ds_read_b128 v[120:123], v188 offset:64
	s_waitcnt lgkmcnt(14)
	v_mfma_f32_32x32x16_bf16 a[32:47], v[68:71], v[80:83], a[32:47]
	global_load_dwordx4 v[238:241], v203, s[100:101] offset:512
	s_waitcnt lgkmcnt(12)
	v_mfma_f32_32x32x16_bf16 a[48:63], v[68:71], v[84:87], a[48:63]
	s_waitcnt vmcnt(11)
	ds_write_b128 v186, v[234:237] offset:18432
	v_mfma_f32_32x32x16_bf16 a[64:79], v[72:75], v[80:83], a[64:79]
	global_load_dwordx4 v[234:237], v202, s[100:101] offset:512
	v_mfma_f32_32x32x16_bf16 a[96:111], v[72:75], v[84:87], a[96:111]
	s_waitcnt vmcnt(11)
	ds_write_b128 v186, v[230:233] offset:23040
	s_waitcnt lgkmcnt(13)
	v_mfma_f32_32x32x16_bf16 a[80:95], v[76:79], v[80:83], a[80:95]
	global_load_dwordx4 v[230:233], v201, s[100:101] offset:512
	v_mfma_f32_32x32x16_bf16 a[112:127], v[76:79], v[84:87], a[112:127]
	s_waitcnt vmcnt(11)
	ds_write_b128 v186, v[226:229] offset:27648
	s_waitcnt lgkmcnt(13)
	v_mfma_f32_32x32x16_bf16 a[16:31], v[104:107], v[80:83], a[16:31]
	global_load_dwordx4 v[226:229], v200, s[100:101] offset:512
	v_mfma_f32_32x32x16_bf16 a[0:15], v[104:107], v[84:87], a[0:15]
	s_waitcnt vmcnt(11)
	ds_write_b128 v186, v[222:225] offset:32256
	ds_read_b128 v[68:71], v189 offset:96
	ds_read_b128 v[80:83], v187 offset:36960
	ds_read_b128 v[72:75], v189 offset:4704
	ds_read_b128 v[84:87], v187 offset:41568
	ds_read_b128 v[76:79], v189 offset:9312
	ds_read_b128 v[104:107], v188 offset:96
	s_waitcnt lgkmcnt(14)
	v_mfma_f32_32x32x16_bf16 a[32:47], v[108:111], v[14:17], a[32:47]
	global_load_dwordx4 v[222:225], v199, s[100:101] offset:512
	s_waitcnt lgkmcnt(12)
	v_mfma_f32_32x32x16_bf16 a[48:63], v[108:111], v[64:67], a[48:63]
	s_waitcnt vmcnt(11)
	ds_write_b128 v186, v[218:221] offset:36864
	v_mfma_f32_32x32x16_bf16 a[64:79], v[112:115], v[14:17], a[64:79]
	global_load_dwordx4 v[218:221], v198, s[98:99] offset:256
	v_mfma_f32_32x32x16_bf16 a[96:111], v[112:115], v[64:67], a[96:111]
	s_waitcnt vmcnt(11)
	ds_write_b128 v186, v[214:217] offset:41472
	s_waitcnt lgkmcnt(13)
	v_mfma_f32_32x32x16_bf16 a[80:95], v[116:119], v[14:17], a[80:95]
	global_load_dwordx4 v[214:217], v197, s[98:99] offset:256
	v_mfma_f32_32x32x16_bf16 a[112:127], v[116:119], v[64:67], a[112:127]
	s_waitcnt vmcnt(11)
	ds_write_b128 v186, v[210:213] offset:46080
	s_waitcnt lgkmcnt(13)
	v_mfma_f32_32x32x16_bf16 a[16:31], v[120:123], v[14:17], a[16:31]
	global_load_dwordx4 v[210:213], v196, s[98:99] offset:256
	v_mfma_f32_32x32x16_bf16 a[0:15], v[120:123], v[64:67], a[0:15]
	s_waitcnt vmcnt(11)
	ds_write_b128 v186, v[206:209] offset:50688
	s_waitcnt lgkmcnt(0)
	v_mfma_f32_32x32x16_bf16 a[32:47], v[68:71], v[80:83], a[32:47]
	global_load_dwordx4 v[206:209], v195, s[98:99] offset:256
	s_add_u32 s100, s100, 0x80
	s_addc_u32 s101, s101, 0
	s_add_u32 s98, s98, 0x80
	s_addc_u32 s99, s99, 0
	v_mfma_f32_32x32x16_bf16 a[48:63], v[68:71], v[84:87], a[48:63]
	v_mfma_f32_32x32x16_bf16 a[64:79], v[72:75], v[80:83], a[64:79]
	v_mfma_f32_32x32x16_bf16 a[96:111], v[72:75], v[84:87], a[96:111]
	s_barrier
	v_add_u32_e32 v189, s50, v192
	v_add_u32_e32 v188, s50, v191
	v_add_u32_e32 v187, s50, v190
	ds_read_b128 v[108:111], v189
	ds_read_b128 v[14:17], v187 offset:36864
	ds_read_b128 v[112:115], v189 offset:4608
	ds_read_b128 v[64:67], v187 offset:41472
	ds_read_b128 v[116:119], v189 offset:9216
	ds_read_b128 v[120:123], v188
	v_mfma_f32_32x32x16_bf16 a[80:95], v[76:79], v[80:83], a[80:95]
	v_mfma_f32_32x32x16_bf16 a[112:127], v[76:79], v[84:87], a[112:127]
	v_mfma_f32_32x32x16_bf16 a[16:31], v[104:107], v[80:83], a[16:31]
	v_mfma_f32_32x32x16_bf16 a[0:15], v[104:107], v[84:87], a[0:15]
	s_add_u32 s44, s44, 0x80
	s_addc_u32 s45, s45, 0
	s_cmpk_lg_i32 s44, 0x700
	s_cbranch_scc1 xg5_varB_4

.LBB0_1462:
	s_and_b32 s5, s4, 1
	s_mul_i32 s8, s5, 0xd800
	s_xor_b32 s5, s5, 1
	s_mul_i32 s5, s5, 0xd800
	s_add_i32 s4, s4, 1
	v_add_u32_e32 v186, s5, v152
	ds_read_b128 v[16:19], v189 offset:32
	ds_read_b128 v[28:31], v187 offset:36896
	ds_read_b128 v[20:23], v189 offset:4640
	ds_read_b128 v[32:35], v187 offset:41504
	ds_read_b128 v[24:27], v189 offset:9248
	ds_read_b128 v[0:3], v188 offset:32
	s_waitcnt lgkmcnt(10)
	v_mfma_f32_32x32x16_bf16 a[32:47], v[52:55], v[8:11], a[32:47]
	s_waitcnt vmcnt(11)
	ds_write_b128 v186, v[250:253]
	s_waitcnt lgkmcnt(9)
	v_mfma_f32_32x32x16_bf16 a[48:63], v[52:55], v[12:15], a[48:63]
	global_load_dwordx4 v[250:253], v254, s[100:101] offset:512
	v_mfma_f32_32x32x16_bf16 a[64:79], v[56:59], v[8:11], a[64:79]
	s_waitcnt vmcnt(11)
	ds_write_b128 v186, v[246:249] offset:4608
	v_mfma_f32_32x32x16_bf16 a[96:111], v[56:59], v[12:15], a[96:111]
	global_load_dwordx4 v[246:249], v205, s[100:101] offset:512
	s_waitcnt lgkmcnt(9)
	v_mfma_f32_32x32x16_bf16 a[80:95], v[60:63], v[8:11], a[80:95]
	s_waitcnt vmcnt(11)
	ds_write_b128 v186, v[242:245] offset:9216
	v_mfma_f32_32x32x16_bf16 a[112:127], v[60:63], v[12:15], a[112:127]
	global_load_dwordx4 v[242:245], v204, s[100:101] offset:512
	s_waitcnt lgkmcnt(9)
	v_mfma_f32_32x32x16_bf16 a[16:31], v[64:67], v[8:11], a[16:31]
	s_waitcnt vmcnt(11)
	ds_write_b128 v186, v[238:241] offset:13824
	v_mfma_f32_32x32x16_bf16 a[0:15], v[64:67], v[12:15], a[0:15]
	global_load_dwordx4 v[238:241], v203, s[100:101] offset:512
	ds_read_b128 v[52:55], v189 offset:64
	ds_read_b128 v[8:11], v187 offset:36928
	ds_read_b128 v[56:59], v189 offset:4672
	ds_read_b128 v[12:15], v187 offset:41536
	ds_read_b128 v[60:63], v189 offset:9280
	ds_read_b128 v[64:67], v188 offset:64
	s_waitcnt lgkmcnt(14)
	v_mfma_f32_32x32x16_bf16 a[32:47], v[16:19], v[28:31], a[32:47]
	s_waitcnt vmcnt(11)
	ds_write_b128 v186, v[234:237] offset:18432
	s_waitcnt lgkmcnt(13)
	v_mfma_f32_32x32x16_bf16 a[48:63], v[16:19], v[32:35], a[48:63]
	global_load_dwordx4 v[234:237], v202, s[100:101] offset:512
	v_mfma_f32_32x32x16_bf16 a[64:79], v[20:23], v[28:31], a[64:79]
	s_waitcnt vmcnt(11)
	ds_write_b128 v186, v[230:233] offset:23040
	v_mfma_f32_32x32x16_bf16 a[96:111], v[20:23], v[32:35], a[96:111]
	global_load_dwordx4 v[230:233], v201, s[100:101] offset:512
	s_waitcnt lgkmcnt(13)
	v_mfma_f32_32x32x16_bf16 a[80:95], v[24:27], v[28:31], a[80:95]
	s_waitcnt vmcnt(11)
	ds_write_b128 v186, v[226:229] offset:27648
	v_mfma_f32_32x32x16_bf16 a[112:127], v[24:27], v[32:35], a[112:127]
	global_load_dwordx4 v[226:229], v200, s[100:101] offset:512
	s_waitcnt lgkmcnt(13)
	v_mfma_f32_32x32x16_bf16 a[16:31], v[0:3], v[28:31], a[16:31]
	s_waitcnt vmcnt(11)
	ds_write_b128 v186, v[222:225] offset:32256
	v_mfma_f32_32x32x16_bf16 a[0:15], v[0:3], v[32:35], a[0:15]
	global_load_dwordx4 v[222:225], v199, s[100:101] offset:512
	ds_read_b128 v[16:19], v189 offset:96
	ds_read_b128 v[28:31], v187 offset:36960
	ds_read_b128 v[20:23], v189 offset:4704
	ds_read_b128 v[32:35], v187 offset:41568
	ds_read_b128 v[24:27], v189 offset:9312
	ds_read_b128 v[0:3], v188 offset:96
	s_waitcnt lgkmcnt(14)
	v_mfma_f32_32x32x16_bf16 a[32:47], v[52:55], v[8:11], a[32:47]
	s_waitcnt vmcnt(11)
	ds_write_b128 v186, v[218:221] offset:36864
	s_waitcnt lgkmcnt(13)
	v_mfma_f32_32x32x16_bf16 a[48:63], v[52:55], v[12:15], a[48:63]
	global_load_dwordx4 v[218:221], v198, s[98:99] offset:256
	v_mfma_f32_32x32x16_bf16 a[64:79], v[56:59], v[8:11], a[64:79]
	s_waitcnt vmcnt(11)
	ds_write_b128 v186, v[214:217] offset:41472
	v_mfma_f32_32x32x16_bf16 a[96:111], v[56:59], v[12:15], a[96:111]
	global_load_dwordx4 v[214:217], v197, s[98:99] offset:256
	s_waitcnt lgkmcnt(13)
	v_mfma_f32_32x32x16_bf16 a[80:95], v[60:63], v[8:11], a[80:95]
	s_waitcnt vmcnt(11)
	ds_write_b128 v186, v[210:213] offset:46080
	v_mfma_f32_32x32x16_bf16 a[112:127], v[60:63], v[12:15], a[112:127]
	global_load_dwordx4 v[210:213], v196, s[98:99] offset:256
	s_waitcnt lgkmcnt(13)
	v_mfma_f32_32x32x16_bf16 a[16:31], v[64:67], v[8:11], a[16:31]
	s_waitcnt vmcnt(11)
	ds_write_b128 v186, v[206:209] offset:50688
	v_mfma_f32_32x32x16_bf16 a[0:15], v[64:67], v[12:15], a[0:15]
	global_load_dwordx4 v[206:209], v195, s[98:99] offset:256
	s_add_u32 s100, s100, 0x80
	s_addc_u32 s101, s101, 0
	s_add_u32 s98, s98, 0x80
	s_addc_u32 s99, s99, 0
	s_waitcnt lgkmcnt(0)
	v_mfma_f32_32x32x16_bf16 a[32:47], v[16:19], v[28:31], a[32:47]
	v_mfma_f32_32x32x16_bf16 a[48:63], v[16:19], v[32:35], a[48:63]
	v_mfma_f32_32x32x16_bf16 a[64:79], v[20:23], v[28:31], a[64:79]
	v_mfma_f32_32x32x16_bf16 a[96:111], v[20:23], v[32:35], a[96:111]
	s_barrier
	v_add_u32_e32 v189, s5, v192
	v_add_u32_e32 v188, s5, v191
	v_add_u32_e32 v187, s5, v190
	ds_read_b128 v[52:55], v189
	ds_read_b128 v[8:11], v187 offset:36864
	ds_read_b128 v[56:59], v189 offset:4608
	ds_read_b128 v[12:15], v187 offset:41472
	ds_read_b128 v[60:63], v189 offset:9216
	ds_read_b128 v[64:67], v188
	v_mfma_f32_32x32x16_bf16 a[80:95], v[24:27], v[28:31], a[80:95]
	v_mfma_f32_32x32x16_bf16 a[112:127], v[24:27], v[32:35], a[112:127]
	v_mfma_f32_32x32x16_bf16 a[16:31], v[0:3], v[28:31], a[16:31]
	v_mfma_f32_32x32x16_bf16 a[0:15], v[0:3], v[32:35], a[0:15]
	s_add_u32 s2, s2, 0x80
	s_addc_u32 s3, s3, 0
	s_cmpk_lg_i32 s2, 0x700
	s_cbranch_scc1 .LBB0_1462
	s_branch xg5_tail_5
xg5_varB_5:
	s_and_b32 s5, s4, 1
	s_mul_i32 s8, s5, 0xd800
	s_xor_b32 s5, s5, 1
	s_mul_i32 s5, s5, 0xd800
	s_add_i32 s4, s4, 1
	v_add_u32_e32 v186, s5, v152
	ds_read_b128 v[16:19], v189 offset:32
	ds_read_b128 v[28:31], v187 offset:36896
	ds_read_b128 v[20:23], v189 offset:4640
	ds_read_b128 v[32:35], v187 offset:41504
	ds_read_b128 v[24:27], v189 offset:9248
	ds_read_b128 v[0:3], v188 offset:32
	s_waitcnt lgkmcnt(10)
	v_mfma_f32_32x32x16_bf16 a[32:47], v[52:55], v[8:11], a[32:47]
	s_waitcnt lgkmcnt(8)
	v_mfma_f32_32x32x16_bf16 a[48:63], v[52:55], v[12:15], a[48:63]
	s_waitcnt vmcnt(11)
	ds_write_b128 v186, v[250:253]
	v_mfma_f32_32x32x16_bf16 a[64:79], v[56:59], v[8:11], a[64:79]
	global_load_dwordx4 v[250:253], v254, s[100:101] offset:512
	v_mfma_f32_32x32x16_bf16 a[96:111], v[56:59], v[12:15], a[96:111]
	s_waitcnt vmcnt(11)
	ds_write_b128 v186, v[246:249] offset:4608
	s_waitcnt lgkmcnt(9)
	v_mfma_f32_32x32x16_bf16 a[80:95], v[60:63], v[8:11], a[80:95]
	global_load_dwordx4 v[246:249], v205, s[100:101] offset:512
	v_mfma_f32_32x32x16_bf16 a[112:127], v[60:63], v[12:15], a[112:127]
	s_waitcnt vmcnt(11)
	ds_write_b128 v186, v[242:245] offset:9216
	s_waitcnt lgkmcnt(9)
	v_mfma_f32_32x32x16_bf16 a[16:31], v[64:67], v[8:11], a[16:31]
	global_load_dwordx4 v[242:245], v204, s[100:101] offset:512
	v_mfma_f32_32x32x16_bf16 a[0:15], v[64:67], v[12:15], a[0:15]
	s_waitcnt vmcnt(11)
	ds_write_b128 v186, v[238:241] offset:13824
	ds_read_b128 v[52:55], v189 offset:64
	ds_read_b128 v[8:11], v187 offset:36928
	ds_read_b128 v[56:59], v189 offset:4672
	ds_read_b128 v[12:15], v187 offset:41536
	ds_read_b128 v[60:63], v189 offset:9280
	ds_read_b128 v[64:67], v188 offset:64
	s_waitcnt lgkmcnt(14)
	v_mfma_f32_32x32x16_bf16 a[32:47], v[16:19], v[28:31], a[32:47]
	global_load_dwordx4 v[238:241], v203, s[100:101] offset:512
	s_waitcnt lgkmcnt(12)
	v_mfma_f32_32x32x16_bf16 a[48:63], v[16:19], v[32:35], a[48:63]
	s_waitcnt vmcnt(11)
	ds_write_b128 v186, v[234:237] offset:18432
	v_mfma_f32_32x32x16_bf16 a[64:79], v[20:23], v[28:31], a[64:79]
	global_load_dwordx4 v[234:237], v202, s[100:101] offset:512
	v_mfma_f32_32x32x16_bf16 a[96:111], v[20:23], v[32:35], a[96:111]
	s_waitcnt vmcnt(11)
	ds_write_b128 v186, v[230:233] offset:23040
	s_waitcnt lgkmcnt(13)
	v_mfma_f32_32x32x16_bf16 a[80:95], v[24:27], v[28:31], a[80:95]
	global_load_dwordx4 v[230:233], v201, s[100:101] offset:512
	v_mfma_f32_32x32x16_bf16 a[112:127], v[24:27], v[32:35], a[112:127]
	s_waitcnt vmcnt(11)
	ds_write_b128 v186, v[226:229] offset:27648
	s_waitcnt lgkmcnt(13)
	v_mfma_f32_32x32x16_bf16 a[16:31], v[0:3], v[28:31], a[16:31]
	global_load_dwordx4 v[226:229], v200, s[100:101] offset:512
	v_mfma_f32_32x32x16_bf16 a[0:15], v[0:3], v[32:35], a[0:15]
	s_waitcnt vmcnt(11)
	ds_write_b128 v186, v[222:225] offset:32256
	ds_read_b128 v[16:19], v189 offset:96
	ds_read_b128 v[28:31], v187 offset:36960
	ds_read_b128 v[20:23], v189 offset:4704
	ds_read_b128 v[32:35], v187 offset:41568
	ds_read_b128 v[24:27], v189 offset:9312
	ds_read_b128 v[0:3], v188 offset:96
	s_waitcnt lgkmcnt(14)
	v_mfma_f32_32x32x16_bf16 a[32:47], v[52:55], v[8:11], a[32:47]
	global_load_dwordx4 v[222:225], v199, s[100:101] offset:512
	s_waitcnt lgkmcnt(12)
	v_mfma_f32_32x32x16_bf16 a[48:63], v[52:55], v[12:15], a[48:63]
	s_waitcnt vmcnt(11)
	ds_write_b128 v186, v[218:221] offset:36864
	v_mfma_f32_32x32x16_bf16 a[64:79], v[56:59], v[8:11], a[64:79]
	global_load_dwordx4 v[218:221], v198, s[98:99] offset:256
	v_mfma_f32_32x32x16_bf16 a[96:111], v[56:59], v[12:15], a[96:111]
	s_waitcnt vmcnt(11)
	ds_write_b128 v186, v[214:217] offset:41472
	s_waitcnt lgkmcnt(13)
	v_mfma_f32_32x32x16_bf16 a[80:95], v[60:63], v[8:11], a[80:95]
	global_load_dwordx4 v[214:217], v197, s[98:99] offset:256
	v_mfma_f32_32x32x16_bf16 a[112:127], v[60:63], v[12:15], a[112:127]
	s_waitcnt vmcnt(11)
	ds_write_b128 v186, v[210:213] offset:46080
	s_waitcnt lgkmcnt(13)
	v_mfma_f32_32x32x16_bf16 a[16:31], v[64:67], v[8:11], a[16:31]
	global_load_dwordx4 v[210:213], v196, s[98:99] offset:256
	v_mfma_f32_32x32x16_bf16 a[0:15], v[64:67], v[12:15], a[0:15]
	s_waitcnt vmcnt(11)
	ds_write_b128 v186, v[206:209] offset:50688
	s_waitcnt lgkmcnt(0)
	v_mfma_f32_32x32x16_bf16 a[32:47], v[16:19], v[28:31], a[32:47]
	global_load_dwordx4 v[206:209], v195, s[98:99] offset:256
	s_add_u32 s100, s100, 0x80
	s_addc_u32 s101, s101, 0
	s_add_u32 s98, s98, 0x80
	s_addc_u32 s99, s99, 0
	v_mfma_f32_32x32x16_bf16 a[48:63], v[16:19], v[32:35], a[48:63]
	v_mfma_f32_32x32x16_bf16 a[64:79], v[20:23], v[28:31], a[64:79]
	v_mfma_f32_32x32x16_bf16 a[96:111], v[20:23], v[32:35], a[96:111]
	s_barrier
	v_add_u32_e32 v189, s5, v192
	v_add_u32_e32 v188, s5, v191
	v_add_u32_e32 v187, s5, v190
	ds_read_b128 v[52:55], v189
	ds_read_b128 v[8:11], v187 offset:36864
	ds_read_b128 v[56:59], v189 offset:4608
	ds_read_b128 v[12:15], v187 offset:41472
	ds_read_b128 v[60:63], v189 offset:9216
	ds_read_b128 v[64:67], v188
	v_mfma_f32_32x32x16_bf16 a[80:95], v[24:27], v[28:31], a[80:95]
	v_mfma_f32_32x32x16_bf16 a[112:127], v[24:27], v[32:35], a[112:127]
	v_mfma_f32_32x32x16_bf16 a[16:31], v[0:3], v[28:31], a[16:31]
	v_mfma_f32_32x32x16_bf16 a[0:15], v[0:3], v[32:35], a[0:15]
	s_add_u32 s2, s2, 0x80
	s_addc_u32 s3, s3, 0
	s_cmpk_lg_i32 s2, 0x700
	s_cbranch_scc1 xg5_varB_5

.LBB0_1964:
	s_and_b32 s50, s42, 1
	s_mul_i32 s51, s50, 0xd800
	s_xor_b32 s50, s50, 1
	s_mul_i32 s50, s50, 0xd800
	s_add_i32 s42, s42, 1
	v_add_u32_e32 v186, s50, v45
	ds_read_b128 v[68:71], v189 offset:32
	ds_read_b128 v[80:83], v187 offset:36896
	ds_read_b128 v[72:75], v189 offset:4640
	ds_read_b128 v[84:87], v187 offset:41504
	ds_read_b128 v[76:79], v189 offset:9248
	ds_read_b128 v[104:107], v188 offset:32
	s_waitcnt lgkmcnt(10)
	v_mfma_f32_32x32x16_bf16 a[32:47], v[108:111], v[14:17], a[32:47]
	s_waitcnt vmcnt(11)
	ds_write_b128 v186, v[250:253]
	s_waitcnt lgkmcnt(9)
	v_mfma_f32_32x32x16_bf16 a[48:63], v[108:111], v[64:67], a[48:63]
	global_load_dwordx4 v[250:253], v254, s[100:101] offset:512
	v_mfma_f32_32x32x16_bf16 a[64:79], v[112:115], v[14:17], a[64:79]
	s_waitcnt vmcnt(11)
	ds_write_b128 v186, v[246:249] offset:4608
	v_mfma_f32_32x32x16_bf16 a[96:111], v[112:115], v[64:67], a[96:111]
	global_load_dwordx4 v[246:249], v205, s[100:101] offset:512
	s_waitcnt lgkmcnt(9)
	v_mfma_f32_32x32x16_bf16 a[80:95], v[116:119], v[14:17], a[80:95]
	s_waitcnt vmcnt(11)
	ds_write_b128 v186, v[242:245] offset:9216
	v_mfma_f32_32x32x16_bf16 a[112:127], v[116:119], v[64:67], a[112:127]
	global_load_dwordx4 v[242:245], v204, s[100:101] offset:512
	s_waitcnt lgkmcnt(9)
	v_mfma_f32_32x32x16_bf16 a[16:31], v[120:123], v[14:17], a[16:31]
	s_waitcnt vmcnt(11)
	ds_write_b128 v186, v[238:241] offset:13824
	v_mfma_f32_32x32x16_bf16 a[0:15], v[120:123], v[64:67], a[0:15]
	global_load_dwordx4 v[238:241], v203, s[100:101] offset:512
	ds_read_b128 v[108:111], v189 offset:64
	ds_read_b128 v[14:17], v187 offset:36928
	ds_read_b128 v[112:115], v189 offset:4672
	ds_read_b128 v[64:67], v187 offset:41536
	ds_read_b128 v[116:119], v189 offset:9280
	ds_read_b128 v[120:123], v188 offset:64
	s_waitcnt lgkmcnt(14)
	v_mfma_f32_32x32x16_bf16 a[32:47], v[68:71], v[80:83], a[32:47]
	s_waitcnt vmcnt(11)
	ds_write_b128 v186, v[234:237] offset:18432
	s_waitcnt lgkmcnt(13)
	v_mfma_f32_32x32x16_bf16 a[48:63], v[68:71], v[84:87], a[48:63]
	global_load_dwordx4 v[234:237], v202, s[100:101] offset:512
	v_mfma_f32_32x32x16_bf16 a[64:79], v[72:75], v[80:83], a[64:79]
	s_waitcnt vmcnt(11)
	ds_write_b128 v186, v[230:233] offset:23040
	v_mfma_f32_32x32x16_bf16 a[96:111], v[72:75], v[84:87], a[96:111]
	global_load_dwordx4 v[230:233], v201, s[100:101] offset:512
	s_waitcnt lgkmcnt(13)
	v_mfma_f32_32x32x16_bf16 a[80:95], v[76:79], v[80:83], a[80:95]
	s_waitcnt vmcnt(11)
	ds_write_b128 v186, v[226:229] offset:27648
	v_mfma_f32_32x32x16_bf16 a[112:127], v[76:79], v[84:87], a[112:127]
	global_load_dwordx4 v[226:229], v200, s[100:101] offset:512
	s_waitcnt lgkmcnt(13)
	v_mfma_f32_32x32x16_bf16 a[16:31], v[104:107], v[80:83], a[16:31]
	s_waitcnt vmcnt(11)
	ds_write_b128 v186, v[222:225] offset:32256
	v_mfma_f32_32x32x16_bf16 a[0:15], v[104:107], v[84:87], a[0:15]
	global_load_dwordx4 v[222:225], v199, s[100:101] offset:512
	ds_read_b128 v[68:71], v189 offset:96
	ds_read_b128 v[80:83], v187 offset:36960
	ds_read_b128 v[72:75], v189 offset:4704
	ds_read_b128 v[84:87], v187 offset:41568
	ds_read_b128 v[76:79], v189 offset:9312
	ds_read_b128 v[104:107], v188 offset:96
	s_waitcnt lgkmcnt(14)
	v_mfma_f32_32x32x16_bf16 a[32:47], v[108:111], v[14:17], a[32:47]
	s_waitcnt vmcnt(11)
	ds_write_b128 v186, v[218:221] offset:36864
	s_waitcnt lgkmcnt(13)
	v_mfma_f32_32x32x16_bf16 a[48:63], v[108:111], v[64:67], a[48:63]
	global_load_dwordx4 v[218:221], v198, s[98:99] offset:256
	v_mfma_f32_32x32x16_bf16 a[64:79], v[112:115], v[14:17], a[64:79]
	s_waitcnt vmcnt(11)
	ds_write_b128 v186, v[214:217] offset:41472
	v_mfma_f32_32x32x16_bf16 a[96:111], v[112:115], v[64:67], a[96:111]
	global_load_dwordx4 v[214:217], v197, s[98:99] offset:256
	s_waitcnt lgkmcnt(13)
	v_mfma_f32_32x32x16_bf16 a[80:95], v[116:119], v[14:17], a[80:95]
	s_waitcnt vmcnt(11)
	ds_write_b128 v186, v[210:213] offset:46080
	v_mfma_f32_32x32x16_bf16 a[112:127], v[116:119], v[64:67], a[112:127]
	global_load_dwordx4 v[210:213], v196, s[98:99] offset:256
	s_waitcnt lgkmcnt(13)
	v_mfma_f32_32x32x16_bf16 a[16:31], v[120:123], v[14:17], a[16:31]
	s_waitcnt vmcnt(11)
	ds_write_b128 v186, v[206:209] offset:50688
	v_mfma_f32_32x32x16_bf16 a[0:15], v[120:123], v[64:67], a[0:15]
	global_load_dwordx4 v[206:209], v195, s[98:99] offset:256
	s_add_u32 s100, s100, 0x80
	s_addc_u32 s101, s101, 0
	s_add_u32 s98, s98, 0x80
	s_addc_u32 s99, s99, 0
	s_waitcnt lgkmcnt(0)
	v_mfma_f32_32x32x16_bf16 a[32:47], v[68:71], v[80:83], a[32:47]
	v_mfma_f32_32x32x16_bf16 a[48:63], v[68:71], v[84:87], a[48:63]
	v_mfma_f32_32x32x16_bf16 a[64:79], v[72:75], v[80:83], a[64:79]
	v_mfma_f32_32x32x16_bf16 a[96:111], v[72:75], v[84:87], a[96:111]
	s_barrier
	v_add_u32_e32 v189, s50, v192
	v_add_u32_e32 v188, s50, v191
	v_add_u32_e32 v187, s50, v190
	ds_read_b128 v[108:111], v189
	ds_read_b128 v[14:17], v187 offset:36864
	ds_read_b128 v[112:115], v189 offset:4608
	ds_read_b128 v[64:67], v187 offset:41472
	ds_read_b128 v[116:119], v189 offset:9216
	ds_read_b128 v[120:123], v188
	v_mfma_f32_32x32x16_bf16 a[80:95], v[76:79], v[80:83], a[80:95]
	v_mfma_f32_32x32x16_bf16 a[112:127], v[76:79], v[84:87], a[112:127]
	v_mfma_f32_32x32x16_bf16 a[16:31], v[104:107], v[80:83], a[16:31]
	v_mfma_f32_32x32x16_bf16 a[0:15], v[104:107], v[84:87], a[0:15]
	s_add_u32 s44, s44, 0x80
	s_addc_u32 s45, s45, 0
	s_cmpk_lg_i32 s44, 0x700
	s_cbranch_scc1 .LBB0_1964
	s_branch xg5_tail_6
xg5_varB_6:
	s_and_b32 s50, s42, 1
	s_mul_i32 s51, s50, 0xd800
	s_xor_b32 s50, s50, 1
	s_mul_i32 s50, s50, 0xd800
	s_add_i32 s42, s42, 1
	v_add_u32_e32 v186, s50, v45
	ds_read_b128 v[68:71], v189 offset:32
	ds_read_b128 v[80:83], v187 offset:36896
	ds_read_b128 v[72:75], v189 offset:4640
	ds_read_b128 v[84:87], v187 offset:41504
	ds_read_b128 v[76:79], v189 offset:9248
	ds_read_b128 v[104:107], v188 offset:32
	s_waitcnt lgkmcnt(10)
	v_mfma_f32_32x32x16_bf16 a[32:47], v[108:111], v[14:17], a[32:47]
	s_waitcnt lgkmcnt(8)
	v_mfma_f32_32x32x16_bf16 a[48:63], v[108:111], v[64:67], a[48:63]
	s_waitcnt vmcnt(11)
	ds_write_b128 v186, v[250:253]
	v_mfma_f32_32x32x16_bf16 a[64:79], v[112:115], v[14:17], a[64:79]
	global_load_dwordx4 v[250:253], v254, s[100:101] offset:512
	v_mfma_f32_32x32x16_bf16 a[96:111], v[112:115], v[64:67], a[96:111]
	s_waitcnt vmcnt(11)
	ds_write_b128 v186, v[246:249] offset:4608
	s_waitcnt lgkmcnt(9)
	v_mfma_f32_32x32x16_bf16 a[80:95], v[116:119], v[14:17], a[80:95]
	global_load_dwordx4 v[246:249], v205, s[100:101] offset:512
	v_mfma_f32_32x32x16_bf16 a[112:127], v[116:119], v[64:67], a[112:127]
	s_waitcnt vmcnt(11)
	ds_write_b128 v186, v[242:245] offset:9216
	s_waitcnt lgkmcnt(9)
	v_mfma_f32_32x32x16_bf16 a[16:31], v[120:123], v[14:17], a[16:31]
	global_load_dwordx4 v[242:245], v204, s[100:101] offset:512
	v_mfma_f32_32x32x16_bf16 a[0:15], v[120:123], v[64:67], a[0:15]
	s_waitcnt vmcnt(11)
	ds_write_b128 v186, v[238:241] offset:13824
	ds_read_b128 v[108:111], v189 offset:64
	ds_read_b128 v[14:17], v187 offset:36928
	ds_read_b128 v[112:115], v189 offset:4672
	ds_read_b128 v[64:67], v187 offset:41536
	ds_read_b128 v[116:119], v189 offset:9280
	ds_read_b128 v[120:123], v188 offset:64
	s_waitcnt lgkmcnt(14)
	v_mfma_f32_32x32x16_bf16 a[32:47], v[68:71], v[80:83], a[32:47]
	global_load_dwordx4 v[238:241], v203, s[100:101] offset:512
	s_waitcnt lgkmcnt(12)
	v_mfma_f32_32x32x16_bf16 a[48:63], v[68:71], v[84:87], a[48:63]
	s_waitcnt vmcnt(11)
	ds_write_b128 v186, v[234:237] offset:18432
	v_mfma_f32_32x32x16_bf16 a[64:79], v[72:75], v[80:83], a[64:79]
	global_load_dwordx4 v[234:237], v202, s[100:101] offset:512
	v_mfma_f32_32x32x16_bf16 a[96:111], v[72:75], v[84:87], a[96:111]
	s_waitcnt vmcnt(11)
	ds_write_b128 v186, v[230:233] offset:23040
	s_waitcnt lgkmcnt(13)
	v_mfma_f32_32x32x16_bf16 a[80:95], v[76:79], v[80:83], a[80:95]
	global_load_dwordx4 v[230:233], v201, s[100:101] offset:512
	v_mfma_f32_32x32x16_bf16 a[112:127], v[76:79], v[84:87], a[112:127]
	s_waitcnt vmcnt(11)
	ds_write_b128 v186, v[226:229] offset:27648
	s_waitcnt lgkmcnt(13)
	v_mfma_f32_32x32x16_bf16 a[16:31], v[104:107], v[80:83], a[16:31]
	global_load_dwordx4 v[226:229], v200, s[100:101] offset:512
	v_mfma_f32_32x32x16_bf16 a[0:15], v[104:107], v[84:87], a[0:15]
	s_waitcnt vmcnt(11)
	ds_write_b128 v186, v[222:225] offset:32256
	ds_read_b128 v[68:71], v189 offset:96
	ds_read_b128 v[80:83], v187 offset:36960
	ds_read_b128 v[72:75], v189 offset:4704
	ds_read_b128 v[84:87], v187 offset:41568
	ds_read_b128 v[76:79], v189 offset:9312
	ds_read_b128 v[104:107], v188 offset:96
	s_waitcnt lgkmcnt(14)
	v_mfma_f32_32x32x16_bf16 a[32:47], v[108:111], v[14:17], a[32:47]
	global_load_dwordx4 v[222:225], v199, s[100:101] offset:512
	s_waitcnt lgkmcnt(12)
	v_mfma_f32_32x32x16_bf16 a[48:63], v[108:111], v[64:67], a[48:63]
	s_waitcnt vmcnt(11)
	ds_write_b128 v186, v[218:221] offset:36864
	v_mfma_f32_32x32x16_bf16 a[64:79], v[112:115], v[14:17], a[64:79]
	global_load_dwordx4 v[218:221], v198, s[98:99] offset:256
	v_mfma_f32_32x32x16_bf16 a[96:111], v[112:115], v[64:67], a[96:111]
	s_waitcnt vmcnt(11)
	ds_write_b128 v186, v[214:217] offset:41472
	s_waitcnt lgkmcnt(13)
	v_mfma_f32_32x32x16_bf16 a[80:95], v[116:119], v[14:17], a[80:95]
	global_load_dwordx4 v[214:217], v197, s[98:99] offset:256
	v_mfma_f32_32x32x16_bf16 a[112:127], v[116:119], v[64:67], a[112:127]
	s_waitcnt vmcnt(11)
	ds_write_b128 v186, v[210:213] offset:46080
	s_waitcnt lgkmcnt(13)
	v_mfma_f32_32x32x16_bf16 a[16:31], v[120:123], v[14:17], a[16:31]
	global_load_dwordx4 v[210:213], v196, s[98:99] offset:256
	v_mfma_f32_32x32x16_bf16 a[0:15], v[120:123], v[64:67], a[0:15]
	s_waitcnt vmcnt(11)
	ds_write_b128 v186, v[206:209] offset:50688
	s_waitcnt lgkmcnt(0)
	v_mfma_f32_32x32x16_bf16 a[32:47], v[68:71], v[80:83], a[32:47]
	global_load_dwordx4 v[206:209], v195, s[98:99] offset:256
	s_add_u32 s100, s100, 0x80
	s_addc_u32 s101, s101, 0
	s_add_u32 s98, s98, 0x80
	s_addc_u32 s99, s99, 0
	v_mfma_f32_32x32x16_bf16 a[48:63], v[68:71], v[84:87], a[48:63]
	v_mfma_f32_32x32x16_bf16 a[64:79], v[72:75], v[80:83], a[64:79]
	v_mfma_f32_32x32x16_bf16 a[96:111], v[72:75], v[84:87], a[96:111]
	s_barrier
	v_add_u32_e32 v189, s50, v192
	v_add_u32_e32 v188, s50, v191
	v_add_u32_e32 v187, s50, v190
	ds_read_b128 v[108:111], v189
	ds_read_b128 v[14:17], v187 offset:36864
	ds_read_b128 v[112:115], v189 offset:4608
	ds_read_b128 v[64:67], v187 offset:41472
	ds_read_b128 v[116:119], v189 offset:9216
	ds_read_b128 v[120:123], v188
	v_mfma_f32_32x32x16_bf16 a[80:95], v[76:79], v[80:83], a[80:95]
	v_mfma_f32_32x32x16_bf16 a[112:127], v[76:79], v[84:87], a[112:127]
	v_mfma_f32_32x32x16_bf16 a[16:31], v[104:107], v[80:83], a[16:31]
	v_mfma_f32_32x32x16_bf16 a[0:15], v[104:107], v[84:87], a[0:15]
	s_add_u32 s44, s44, 0x80
	s_addc_u32 s45, s45, 0
	s_cmpk_lg_i32 s44, 0x700
	s_cbranch_scc1 xg5_varB_6

.LBB0_2161:
	s_and_b32 s4, s10, 1
	s_mul_i32 s11, s4, 0xd800
	s_xor_b32 s4, s4, 1
	s_mul_i32 s4, s4, 0xd800
	s_add_i32 s10, s10, 1
	v_add_u32_e32 v186, s4, v130
	ds_read_b128 v[12:15], v189 offset:32
	ds_read_b128 v[24:27], v187 offset:36896
	ds_read_b128 v[16:19], v189 offset:4640
	ds_read_b128 v[28:31], v187 offset:41504
	ds_read_b128 v[20:23], v189 offset:9248
	ds_read_b128 v[76:79], v188 offset:32
	s_waitcnt lgkmcnt(10)
	v_mfma_f32_32x32x16_bf16 a[32:47], v[80:83], v[4:7], a[32:47]
	s_waitcnt vmcnt(11)
	ds_write_b128 v186, v[250:253]
	s_waitcnt lgkmcnt(9)
	v_mfma_f32_32x32x16_bf16 a[48:63], v[80:83], v[8:11], a[48:63]
	global_load_dwordx4 v[250:253], v254, s[100:101] offset:512
	v_mfma_f32_32x32x16_bf16 a[64:79], v[84:87], v[4:7], a[64:79]
	s_waitcnt vmcnt(11)
	ds_write_b128 v186, v[246:249] offset:4608
	v_mfma_f32_32x32x16_bf16 a[96:111], v[84:87], v[8:11], a[96:111]
	global_load_dwordx4 v[246:249], v205, s[100:101] offset:512
	s_waitcnt lgkmcnt(9)
	v_mfma_f32_32x32x16_bf16 a[80:95], v[88:91], v[4:7], a[80:95]
	s_waitcnt vmcnt(11)
	ds_write_b128 v186, v[242:245] offset:9216
	v_mfma_f32_32x32x16_bf16 a[112:127], v[88:91], v[8:11], a[112:127]
	global_load_dwordx4 v[242:245], v204, s[100:101] offset:512
	s_waitcnt lgkmcnt(9)
	v_mfma_f32_32x32x16_bf16 a[16:31], v[92:95], v[4:7], a[16:31]
	s_waitcnt vmcnt(11)
	ds_write_b128 v186, v[238:241] offset:13824
	v_mfma_f32_32x32x16_bf16 a[0:15], v[92:95], v[8:11], a[0:15]
	global_load_dwordx4 v[238:241], v203, s[100:101] offset:512
	ds_read_b128 v[80:83], v189 offset:64
	ds_read_b128 v[4:7], v187 offset:36928
	ds_read_b128 v[84:87], v189 offset:4672
	ds_read_b128 v[8:11], v187 offset:41536
	ds_read_b128 v[88:91], v189 offset:9280
	ds_read_b128 v[92:95], v188 offset:64
	s_waitcnt lgkmcnt(14)
	v_mfma_f32_32x32x16_bf16 a[32:47], v[12:15], v[24:27], a[32:47]
	s_waitcnt vmcnt(11)
	ds_write_b128 v186, v[234:237] offset:18432
	s_waitcnt lgkmcnt(13)
	v_mfma_f32_32x32x16_bf16 a[48:63], v[12:15], v[28:31], a[48:63]
	global_load_dwordx4 v[234:237], v202, s[100:101] offset:512
	v_mfma_f32_32x32x16_bf16 a[64:79], v[16:19], v[24:27], a[64:79]
	s_waitcnt vmcnt(11)
	ds_write_b128 v186, v[230:233] offset:23040
	v_mfma_f32_32x32x16_bf16 a[96:111], v[16:19], v[28:31], a[96:111]
	global_load_dwordx4 v[230:233], v201, s[100:101] offset:512
	s_waitcnt lgkmcnt(13)
	v_mfma_f32_32x32x16_bf16 a[80:95], v[20:23], v[24:27], a[80:95]
	s_waitcnt vmcnt(11)
	ds_write_b128 v186, v[226:229] offset:27648
	v_mfma_f32_32x32x16_bf16 a[112:127], v[20:23], v[28:31], a[112:127]
	global_load_dwordx4 v[226:229], v200, s[100:101] offset:512
	s_waitcnt lgkmcnt(13)
	v_mfma_f32_32x32x16_bf16 a[16:31], v[76:79], v[24:27], a[16:31]
	s_waitcnt vmcnt(11)
	ds_write_b128 v186, v[222:225] offset:32256
	v_mfma_f32_32x32x16_bf16 a[0:15], v[76:79], v[28:31], a[0:15]
	global_load_dwordx4 v[222:225], v199, s[100:101] offset:512
	ds_read_b128 v[12:15], v189 offset:96
	ds_read_b128 v[24:27], v187 offset:36960
	ds_read_b128 v[16:19], v189 offset:4704
	ds_read_b128 v[28:31], v187 offset:41568
	ds_read_b128 v[20:23], v189 offset:9312
	ds_read_b128 v[76:79], v188 offset:96
	s_waitcnt lgkmcnt(14)
	v_mfma_f32_32x32x16_bf16 a[32:47], v[80:83], v[4:7], a[32:47]
	s_waitcnt vmcnt(11)
	ds_write_b128 v186, v[218:221] offset:36864
	s_waitcnt lgkmcnt(13)
	v_mfma_f32_32x32x16_bf16 a[48:63], v[80:83], v[8:11], a[48:63]
	global_load_dwordx4 v[218:221], v198, s[98:99] offset:256
	v_mfma_f32_32x32x16_bf16 a[64:79], v[84:87], v[4:7], a[64:79]
	s_waitcnt vmcnt(11)
	ds_write_b128 v186, v[214:217] offset:41472
	v_mfma_f32_32x32x16_bf16 a[96:111], v[84:87], v[8:11], a[96:111]
	global_load_dwordx4 v[214:217], v197, s[98:99] offset:256
	s_waitcnt lgkmcnt(13)
	v_mfma_f32_32x32x16_bf16 a[80:95], v[88:91], v[4:7], a[80:95]
	s_waitcnt vmcnt(11)
	ds_write_b128 v186, v[210:213] offset:46080
	v_mfma_f32_32x32x16_bf16 a[112:127], v[88:91], v[8:11], a[112:127]
	global_load_dwordx4 v[210:213], v196, s[98:99] offset:256
	s_waitcnt lgkmcnt(13)
	v_mfma_f32_32x32x16_bf16 a[16:31], v[92:95], v[4:7], a[16:31]
	s_waitcnt vmcnt(11)
	ds_write_b128 v186, v[206:209] offset:50688
	v_mfma_f32_32x32x16_bf16 a[0:15], v[92:95], v[8:11], a[0:15]
	global_load_dwordx4 v[206:209], v195, s[98:99] offset:256
	s_add_u32 s100, s100, 0x80
	s_addc_u32 s101, s101, 0
	s_add_u32 s98, s98, 0x80
	s_addc_u32 s99, s99, 0
	s_waitcnt lgkmcnt(0)
	v_mfma_f32_32x32x16_bf16 a[32:47], v[12:15], v[24:27], a[32:47]
	v_mfma_f32_32x32x16_bf16 a[48:63], v[12:15], v[28:31], a[48:63]
	v_mfma_f32_32x32x16_bf16 a[64:79], v[16:19], v[24:27], a[64:79]
	v_mfma_f32_32x32x16_bf16 a[96:111], v[16:19], v[28:31], a[96:111]
	s_barrier
	v_add_u32_e32 v189, s4, v192
	v_add_u32_e32 v188, s4, v191
	v_add_u32_e32 v187, s4, v190
	ds_read_b128 v[80:83], v189
	ds_read_b128 v[4:7], v187 offset:36864
	ds_read_b128 v[84:87], v189 offset:4608
	ds_read_b128 v[8:11], v187 offset:41472
	ds_read_b128 v[88:91], v189 offset:9216
	ds_read_b128 v[92:95], v188
	v_mfma_f32_32x32x16_bf16 a[80:95], v[20:23], v[24:27], a[80:95]
	v_mfma_f32_32x32x16_bf16 a[112:127], v[20:23], v[28:31], a[112:127]
	v_mfma_f32_32x32x16_bf16 a[16:31], v[76:79], v[24:27], a[16:31]
	v_mfma_f32_32x32x16_bf16 a[0:15], v[76:79], v[28:31], a[0:15]
	s_add_u32 s8, s8, 0x80
	s_addc_u32 s9, s9, 0
	s_cmpk_lg_i32 s8, 0x700
	s_cbranch_scc1 .LBB0_2161
	s_branch xg5_tail_7
xg5_varB_7:
	s_and_b32 s4, s10, 1
	s_mul_i32 s11, s4, 0xd800
	s_xor_b32 s4, s4, 1
	s_mul_i32 s4, s4, 0xd800
	s_add_i32 s10, s10, 1
	v_add_u32_e32 v186, s4, v130
	ds_read_b128 v[12:15], v189 offset:32
	ds_read_b128 v[24:27], v187 offset:36896
	ds_read_b128 v[16:19], v189 offset:4640
	ds_read_b128 v[28:31], v187 offset:41504
	ds_read_b128 v[20:23], v189 offset:9248
	ds_read_b128 v[76:79], v188 offset:32
	s_waitcnt lgkmcnt(10)
	v_mfma_f32_32x32x16_bf16 a[32:47], v[80:83], v[4:7], a[32:47]
	s_waitcnt lgkmcnt(8)
	v_mfma_f32_32x32x16_bf16 a[48:63], v[80:83], v[8:11], a[48:63]
	s_waitcnt vmcnt(11)
	ds_write_b128 v186, v[250:253]
	v_mfma_f32_32x32x16_bf16 a[64:79], v[84:87], v[4:7], a[64:79]
	global_load_dwordx4 v[250:253], v254, s[100:101] offset:512
	v_mfma_f32_32x32x16_bf16 a[96:111], v[84:87], v[8:11], a[96:111]
	s_waitcnt vmcnt(11)
	ds_write_b128 v186, v[246:249] offset:4608
	s_waitcnt lgkmcnt(9)
	v_mfma_f32_32x32x16_bf16 a[80:95], v[88:91], v[4:7], a[80:95]
	global_load_dwordx4 v[246:249], v205, s[100:101] offset:512
	v_mfma_f32_32x32x16_bf16 a[112:127], v[88:91], v[8:11], a[112:127]
	s_waitcnt vmcnt(11)
	ds_write_b128 v186, v[242:245] offset:9216
	s_waitcnt lgkmcnt(9)
	v_mfma_f32_32x32x16_bf16 a[16:31], v[92:95], v[4:7], a[16:31]
	global_load_dwordx4 v[242:245], v204, s[100:101] offset:512
	v_mfma_f32_32x32x16_bf16 a[0:15], v[92:95], v[8:11], a[0:15]
	s_waitcnt vmcnt(11)
	ds_write_b128 v186, v[238:241] offset:13824
	ds_read_b128 v[80:83], v189 offset:64
	ds_read_b128 v[4:7], v187 offset:36928
	ds_read_b128 v[84:87], v189 offset:4672
	ds_read_b128 v[8:11], v187 offset:41536
	ds_read_b128 v[88:91], v189 offset:9280
	ds_read_b128 v[92:95], v188 offset:64
	s_waitcnt lgkmcnt(14)
	v_mfma_f32_32x32x16_bf16 a[32:47], v[12:15], v[24:27], a[32:47]
	global_load_dwordx4 v[238:241], v203, s[100:101] offset:512
	s_waitcnt lgkmcnt(12)
	v_mfma_f32_32x32x16_bf16 a[48:63], v[12:15], v[28:31], a[48:63]
	s_waitcnt vmcnt(11)
	ds_write_b128 v186, v[234:237] offset:18432
	v_mfma_f32_32x32x16_bf16 a[64:79], v[16:19], v[24:27], a[64:79]
	global_load_dwordx4 v[234:237], v202, s[100:101] offset:512
	v_mfma_f32_32x32x16_bf16 a[96:111], v[16:19], v[28:31], a[96:111]
	s_waitcnt vmcnt(11)
	ds_write_b128 v186, v[230:233] offset:23040
	s_waitcnt lgkmcnt(13)
	v_mfma_f32_32x32x16_bf16 a[80:95], v[20:23], v[24:27], a[80:95]
	global_load_dwordx4 v[230:233], v201, s[100:101] offset:512
	v_mfma_f32_32x32x16_bf16 a[112:127], v[20:23], v[28:31], a[112:127]
	s_waitcnt vmcnt(11)
	ds_write_b128 v186, v[226:229] offset:27648
	s_waitcnt lgkmcnt(13)
	v_mfma_f32_32x32x16_bf16 a[16:31], v[76:79], v[24:27], a[16:31]
	global_load_dwordx4 v[226:229], v200, s[100:101] offset:512
	v_mfma_f32_32x32x16_bf16 a[0:15], v[76:79], v[28:31], a[0:15]
	s_waitcnt vmcnt(11)
	ds_write_b128 v186, v[222:225] offset:32256
	ds_read_b128 v[12:15], v189 offset:96
	ds_read_b128 v[24:27], v187 offset:36960
	ds_read_b128 v[16:19], v189 offset:4704
	ds_read_b128 v[28:31], v187 offset:41568
	ds_read_b128 v[20:23], v189 offset:9312
	ds_read_b128 v[76:79], v188 offset:96
	s_waitcnt lgkmcnt(14)
	v_mfma_f32_32x32x16_bf16 a[32:47], v[80:83], v[4:7], a[32:47]
	global_load_dwordx4 v[222:225], v199, s[100:101] offset:512
	s_waitcnt lgkmcnt(12)
	v_mfma_f32_32x32x16_bf16 a[48:63], v[80:83], v[8:11], a[48:63]
	s_waitcnt vmcnt(11)
	ds_write_b128 v186, v[218:221] offset:36864
	v_mfma_f32_32x32x16_bf16 a[64:79], v[84:87], v[4:7], a[64:79]
	global_load_dwordx4 v[218:221], v198, s[98:99] offset:256
	v_mfma_f32_32x32x16_bf16 a[96:111], v[84:87], v[8:11], a[96:111]
	s_waitcnt vmcnt(11)
	ds_write_b128 v186, v[214:217] offset:41472
	s_waitcnt lgkmcnt(13)
	v_mfma_f32_32x32x16_bf16 a[80:95], v[88:91], v[4:7], a[80:95]
	global_load_dwordx4 v[214:217], v197, s[98:99] offset:256
	v_mfma_f32_32x32x16_bf16 a[112:127], v[88:91], v[8:11], a[112:127]
	s_waitcnt vmcnt(11)
	ds_write_b128 v186, v[210:213] offset:46080
	s_waitcnt lgkmcnt(13)
	v_mfma_f32_32x32x16_bf16 a[16:31], v[92:95], v[4:7], a[16:31]
	global_load_dwordx4 v[210:213], v196, s[98:99] offset:256
	v_mfma_f32_32x32x16_bf16 a[0:15], v[92:95], v[8:11], a[0:15]
	s_waitcnt vmcnt(11)
	ds_write_b128 v186, v[206:209] offset:50688
	s_waitcnt lgkmcnt(0)
	v_mfma_f32_32x32x16_bf16 a[32:47], v[12:15], v[24:27], a[32:47]
	global_load_dwordx4 v[206:209], v195, s[98:99] offset:256
	s_add_u32 s100, s100, 0x80
	s_addc_u32 s101, s101, 0
	s_add_u32 s98, s98, 0x80
	s_addc_u32 s99, s99, 0
	v_mfma_f32_32x32x16_bf16 a[48:63], v[12:15], v[28:31], a[48:63]
	v_mfma_f32_32x32x16_bf16 a[64:79], v[16:19], v[24:27], a[64:79]
	v_mfma_f32_32x32x16_bf16 a[96:111], v[16:19], v[28:31], a[96:111]
	s_barrier
	v_add_u32_e32 v189, s4, v192
	v_add_u32_e32 v188, s4, v191
	v_add_u32_e32 v187, s4, v190
	ds_read_b128 v[80:83], v189
	ds_read_b128 v[4:7], v187 offset:36864
	ds_read_b128 v[84:87], v189 offset:4608
	ds_read_b128 v[8:11], v187 offset:41472
	ds_read_b128 v[88:91], v189 offset:9216
	ds_read_b128 v[92:95], v188
	v_mfma_f32_32x32x16_bf16 a[80:95], v[20:23], v[24:27], a[80:95]
	v_mfma_f32_32x32x16_bf16 a[112:127], v[20:23], v[28:31], a[112:127]
	v_mfma_f32_32x32x16_bf16 a[16:31], v[76:79], v[24:27], a[16:31]
	v_mfma_f32_32x32x16_bf16 a[0:15], v[76:79], v[28:31], a[0:15]
	s_add_u32 s8, s8, 0x80
	s_addc_u32 s9, s9, 0
	s_cmpk_lg_i32 s8, 0x700
	s_cbranch_scc1 xg5_varB_7

.LBB0_2449:
	s_and_b32 s50, s42, 1
	s_mul_i32 s51, s50, 0xd800
	s_xor_b32 s50, s50, 1
	s_mul_i32 s50, s50, 0xd800
	s_add_i32 s42, s42, 1
	v_add_u32_e32 v186, s50, v45
	ds_read_b128 v[68:71], v189 offset:32
	ds_read_b128 v[80:83], v187 offset:36896
	ds_read_b128 v[72:75], v189 offset:4640
	ds_read_b128 v[84:87], v187 offset:41504
	ds_read_b128 v[76:79], v189 offset:9248
	ds_read_b128 v[104:107], v188 offset:32
	s_waitcnt lgkmcnt(10)
	v_mfma_f32_32x32x16_bf16 a[32:47], v[108:111], v[14:17], a[32:47]
	s_waitcnt vmcnt(11)
	ds_write_b128 v186, v[250:253]
	s_waitcnt lgkmcnt(9)
	v_mfma_f32_32x32x16_bf16 a[48:63], v[108:111], v[64:67], a[48:63]
	global_load_dwordx4 v[250:253], v254, s[100:101] offset:512
	v_mfma_f32_32x32x16_bf16 a[64:79], v[112:115], v[14:17], a[64:79]
	s_waitcnt vmcnt(11)
	ds_write_b128 v186, v[246:249] offset:4608
	v_mfma_f32_32x32x16_bf16 a[96:111], v[112:115], v[64:67], a[96:111]
	global_load_dwordx4 v[246:249], v205, s[100:101] offset:512
	s_waitcnt lgkmcnt(9)
	v_mfma_f32_32x32x16_bf16 a[80:95], v[116:119], v[14:17], a[80:95]
	s_waitcnt vmcnt(11)
	ds_write_b128 v186, v[242:245] offset:9216
	v_mfma_f32_32x32x16_bf16 a[112:127], v[116:119], v[64:67], a[112:127]
	global_load_dwordx4 v[242:245], v204, s[100:101] offset:512
	s_waitcnt lgkmcnt(9)
	v_mfma_f32_32x32x16_bf16 a[16:31], v[120:123], v[14:17], a[16:31]
	s_waitcnt vmcnt(11)
	ds_write_b128 v186, v[238:241] offset:13824
	v_mfma_f32_32x32x16_bf16 a[0:15], v[120:123], v[64:67], a[0:15]
	global_load_dwordx4 v[238:241], v203, s[100:101] offset:512
	ds_read_b128 v[108:111], v189 offset:64
	ds_read_b128 v[14:17], v187 offset:36928
	ds_read_b128 v[112:115], v189 offset:4672
	ds_read_b128 v[64:67], v187 offset:41536
	ds_read_b128 v[116:119], v189 offset:9280
	ds_read_b128 v[120:123], v188 offset:64
	s_waitcnt lgkmcnt(14)
	v_mfma_f32_32x32x16_bf16 a[32:47], v[68:71], v[80:83], a[32:47]
	s_waitcnt vmcnt(11)
	ds_write_b128 v186, v[234:237] offset:18432
	s_waitcnt lgkmcnt(13)
	v_mfma_f32_32x32x16_bf16 a[48:63], v[68:71], v[84:87], a[48:63]
	global_load_dwordx4 v[234:237], v202, s[100:101] offset:512
	v_mfma_f32_32x32x16_bf16 a[64:79], v[72:75], v[80:83], a[64:79]
	s_waitcnt vmcnt(11)
	ds_write_b128 v186, v[230:233] offset:23040
	v_mfma_f32_32x32x16_bf16 a[96:111], v[72:75], v[84:87], a[96:111]
	global_load_dwordx4 v[230:233], v201, s[100:101] offset:512
	s_waitcnt lgkmcnt(13)
	v_mfma_f32_32x32x16_bf16 a[80:95], v[76:79], v[80:83], a[80:95]
	s_waitcnt vmcnt(11)
	ds_write_b128 v186, v[226:229] offset:27648
	v_mfma_f32_32x32x16_bf16 a[112:127], v[76:79], v[84:87], a[112:127]
	global_load_dwordx4 v[226:229], v200, s[100:101] offset:512
	s_waitcnt lgkmcnt(13)
	v_mfma_f32_32x32x16_bf16 a[16:31], v[104:107], v[80:83], a[16:31]
	s_waitcnt vmcnt(11)
	ds_write_b128 v186, v[222:225] offset:32256
	v_mfma_f32_32x32x16_bf16 a[0:15], v[104:107], v[84:87], a[0:15]
	global_load_dwordx4 v[222:225], v199, s[100:101] offset:512
	ds_read_b128 v[68:71], v189 offset:96
	ds_read_b128 v[80:83], v187 offset:36960
	ds_read_b128 v[72:75], v189 offset:4704
	ds_read_b128 v[84:87], v187 offset:41568
	ds_read_b128 v[76:79], v189 offset:9312
	ds_read_b128 v[104:107], v188 offset:96
	s_waitcnt lgkmcnt(14)
	v_mfma_f32_32x32x16_bf16 a[32:47], v[108:111], v[14:17], a[32:47]
	s_waitcnt vmcnt(11)
	ds_write_b128 v186, v[218:221] offset:36864
	s_waitcnt lgkmcnt(13)
	v_mfma_f32_32x32x16_bf16 a[48:63], v[108:111], v[64:67], a[48:63]
	global_load_dwordx4 v[218:221], v198, s[98:99] offset:256
	v_mfma_f32_32x32x16_bf16 a[64:79], v[112:115], v[14:17], a[64:79]
	s_waitcnt vmcnt(11)
	ds_write_b128 v186, v[214:217] offset:41472
	v_mfma_f32_32x32x16_bf16 a[96:111], v[112:115], v[64:67], a[96:111]
	global_load_dwordx4 v[214:217], v197, s[98:99] offset:256
	s_waitcnt lgkmcnt(13)
	v_mfma_f32_32x32x16_bf16 a[80:95], v[116:119], v[14:17], a[80:95]
	s_waitcnt vmcnt(11)
	ds_write_b128 v186, v[210:213] offset:46080
	v_mfma_f32_32x32x16_bf16 a[112:127], v[116:119], v[64:67], a[112:127]
	global_load_dwordx4 v[210:213], v196, s[98:99] offset:256
	s_waitcnt lgkmcnt(13)
	v_mfma_f32_32x32x16_bf16 a[16:31], v[120:123], v[14:17], a[16:31]
	s_waitcnt vmcnt(11)
	ds_write_b128 v186, v[206:209] offset:50688
	v_mfma_f32_32x32x16_bf16 a[0:15], v[120:123], v[64:67], a[0:15]
	global_load_dwordx4 v[206:209], v195, s[98:99] offset:256
	s_add_u32 s100, s100, 0x80
	s_addc_u32 s101, s101, 0
	s_add_u32 s98, s98, 0x80
	s_addc_u32 s99, s99, 0
	s_waitcnt lgkmcnt(0)
	v_mfma_f32_32x32x16_bf16 a[32:47], v[68:71], v[80:83], a[32:47]
	v_mfma_f32_32x32x16_bf16 a[48:63], v[68:71], v[84:87], a[48:63]
	v_mfma_f32_32x32x16_bf16 a[64:79], v[72:75], v[80:83], a[64:79]
	v_mfma_f32_32x32x16_bf16 a[96:111], v[72:75], v[84:87], a[96:111]
	s_barrier
	v_add_u32_e32 v189, s50, v192
	v_add_u32_e32 v188, s50, v191
	v_add_u32_e32 v187, s50, v190
	ds_read_b128 v[108:111], v189
	ds_read_b128 v[14:17], v187 offset:36864
	ds_read_b128 v[112:115], v189 offset:4608
	ds_read_b128 v[64:67], v187 offset:41472
	ds_read_b128 v[116:119], v189 offset:9216
	ds_read_b128 v[120:123], v188
	v_mfma_f32_32x32x16_bf16 a[80:95], v[76:79], v[80:83], a[80:95]
	v_mfma_f32_32x32x16_bf16 a[112:127], v[76:79], v[84:87], a[112:127]
	v_mfma_f32_32x32x16_bf16 a[16:31], v[104:107], v[80:83], a[16:31]
	v_mfma_f32_32x32x16_bf16 a[0:15], v[104:107], v[84:87], a[0:15]
	s_add_u32 s44, s44, 0x80
	s_addc_u32 s45, s45, 0
	s_cmpk_lg_i32 s44, 0x700
	s_cbranch_scc1 .LBB0_2449
	s_branch xg5_tail_8
xg5_varB_8:
	s_and_b32 s50, s42, 1
	s_mul_i32 s51, s50, 0xd800
	s_xor_b32 s50, s50, 1
	s_mul_i32 s50, s50, 0xd800
	s_add_i32 s42, s42, 1
	v_add_u32_e32 v186, s50, v45
	ds_read_b128 v[68:71], v189 offset:32
	ds_read_b128 v[80:83], v187 offset:36896
	ds_read_b128 v[72:75], v189 offset:4640
	ds_read_b128 v[84:87], v187 offset:41504
	ds_read_b128 v[76:79], v189 offset:9248
	ds_read_b128 v[104:107], v188 offset:32
	s_waitcnt lgkmcnt(10)
	v_mfma_f32_32x32x16_bf16 a[32:47], v[108:111], v[14:17], a[32:47]
	s_waitcnt lgkmcnt(8)
	v_mfma_f32_32x32x16_bf16 a[48:63], v[108:111], v[64:67], a[48:63]
	s_waitcnt vmcnt(11)
	ds_write_b128 v186, v[250:253]
	v_mfma_f32_32x32x16_bf16 a[64:79], v[112:115], v[14:17], a[64:79]
	global_load_dwordx4 v[250:253], v254, s[100:101] offset:512
	v_mfma_f32_32x32x16_bf16 a[96:111], v[112:115], v[64:67], a[96:111]
	s_waitcnt vmcnt(11)
	ds_write_b128 v186, v[246:249] offset:4608
	s_waitcnt lgkmcnt(9)
	v_mfma_f32_32x32x16_bf16 a[80:95], v[116:119], v[14:17], a[80:95]
	global_load_dwordx4 v[246:249], v205, s[100:101] offset:512
	v_mfma_f32_32x32x16_bf16 a[112:127], v[116:119], v[64:67], a[112:127]
	s_waitcnt vmcnt(11)
	ds_write_b128 v186, v[242:245] offset:9216
	s_waitcnt lgkmcnt(9)
	v_mfma_f32_32x32x16_bf16 a[16:31], v[120:123], v[14:17], a[16:31]
	global_load_dwordx4 v[242:245], v204, s[100:101] offset:512
	v_mfma_f32_32x32x16_bf16 a[0:15], v[120:123], v[64:67], a[0:15]
	s_waitcnt vmcnt(11)
	ds_write_b128 v186, v[238:241] offset:13824
	ds_read_b128 v[108:111], v189 offset:64
	ds_read_b128 v[14:17], v187 offset:36928
	ds_read_b128 v[112:115], v189 offset:4672
	ds_read_b128 v[64:67], v187 offset:41536
	ds_read_b128 v[116:119], v189 offset:9280
	ds_read_b128 v[120:123], v188 offset:64
	s_waitcnt lgkmcnt(14)
	v_mfma_f32_32x32x16_bf16 a[32:47], v[68:71], v[80:83], a[32:47]
	global_load_dwordx4 v[238:241], v203, s[100:101] offset:512
	s_waitcnt lgkmcnt(12)
	v_mfma_f32_32x32x16_bf16 a[48:63], v[68:71], v[84:87], a[48:63]
	s_waitcnt vmcnt(11)
	ds_write_b128 v186, v[234:237] offset:18432
	v_mfma_f32_32x32x16_bf16 a[64:79], v[72:75], v[80:83], a[64:79]
	global_load_dwordx4 v[234:237], v202, s[100:101] offset:512
	v_mfma_f32_32x32x16_bf16 a[96:111], v[72:75], v[84:87], a[96:111]
	s_waitcnt vmcnt(11)
	ds_write_b128 v186, v[230:233] offset:23040
	s_waitcnt lgkmcnt(13)
	v_mfma_f32_32x32x16_bf16 a[80:95], v[76:79], v[80:83], a[80:95]
	global_load_dwordx4 v[230:233], v201, s[100:101] offset:512
	v_mfma_f32_32x32x16_bf16 a[112:127], v[76:79], v[84:87], a[112:127]
	s_waitcnt vmcnt(11)
	ds_write_b128 v186, v[226:229] offset:27648
	s_waitcnt lgkmcnt(13)
	v_mfma_f32_32x32x16_bf16 a[16:31], v[104:107], v[80:83], a[16:31]
	global_load_dwordx4 v[226:229], v200, s[100:101] offset:512
	v_mfma_f32_32x32x16_bf16 a[0:15], v[104:107], v[84:87], a[0:15]
	s_waitcnt vmcnt(11)
	ds_write_b128 v186, v[222:225] offset:32256
	ds_read_b128 v[68:71], v189 offset:96
	ds_read_b128 v[80:83], v187 offset:36960
	ds_read_b128 v[72:75], v189 offset:4704
	ds_read_b128 v[84:87], v187 offset:41568
	ds_read_b128 v[76:79], v189 offset:9312
	ds_read_b128 v[104:107], v188 offset:96
	s_waitcnt lgkmcnt(14)
	v_mfma_f32_32x32x16_bf16 a[32:47], v[108:111], v[14:17], a[32:47]
	global_load_dwordx4 v[222:225], v199, s[100:101] offset:512
	s_waitcnt lgkmcnt(12)
	v_mfma_f32_32x32x16_bf16 a[48:63], v[108:111], v[64:67], a[48:63]
	s_waitcnt vmcnt(11)
	ds_write_b128 v186, v[218:221] offset:36864
	v_mfma_f32_32x32x16_bf16 a[64:79], v[112:115], v[14:17], a[64:79]
	global_load_dwordx4 v[218:221], v198, s[98:99] offset:256
	v_mfma_f32_32x32x16_bf16 a[96:111], v[112:115], v[64:67], a[96:111]
	s_waitcnt vmcnt(11)
	ds_write_b128 v186, v[214:217] offset:41472
	s_waitcnt lgkmcnt(13)
	v_mfma_f32_32x32x16_bf16 a[80:95], v[116:119], v[14:17], a[80:95]
	global_load_dwordx4 v[214:217], v197, s[98:99] offset:256
	v_mfma_f32_32x32x16_bf16 a[112:127], v[116:119], v[64:67], a[112:127]
	s_waitcnt vmcnt(11)
	ds_write_b128 v186, v[210:213] offset:46080
	s_waitcnt lgkmcnt(13)
	v_mfma_f32_32x32x16_bf16 a[16:31], v[120:123], v[14:17], a[16:31]
	global_load_dwordx4 v[210:213], v196, s[98:99] offset:256
	v_mfma_f32_32x32x16_bf16 a[0:15], v[120:123], v[64:67], a[0:15]
	s_waitcnt vmcnt(11)
	ds_write_b128 v186, v[206:209] offset:50688
	s_waitcnt lgkmcnt(0)
	v_mfma_f32_32x32x16_bf16 a[32:47], v[68:71], v[80:83], a[32:47]
	global_load_dwordx4 v[206:209], v195, s[98:99] offset:256
	s_add_u32 s100, s100, 0x80
	s_addc_u32 s101, s101, 0
	s_add_u32 s98, s98, 0x80
	s_addc_u32 s99, s99, 0
	v_mfma_f32_32x32x16_bf16 a[48:63], v[68:71], v[84:87], a[48:63]
	v_mfma_f32_32x32x16_bf16 a[64:79], v[72:75], v[80:83], a[64:79]
	v_mfma_f32_32x32x16_bf16 a[96:111], v[72:75], v[84:87], a[96:111]
	s_barrier
	v_add_u32_e32 v189, s50, v192
	v_add_u32_e32 v188, s50, v191
	v_add_u32_e32 v187, s50, v190
	ds_read_b128 v[108:111], v189
	ds_read_b128 v[14:17], v187 offset:36864
	ds_read_b128 v[112:115], v189 offset:4608
	ds_read_b128 v[64:67], v187 offset:41472
	ds_read_b128 v[116:119], v189 offset:9216
	ds_read_b128 v[120:123], v188
	v_mfma_f32_32x32x16_bf16 a[80:95], v[76:79], v[80:83], a[80:95]
	v_mfma_f32_32x32x16_bf16 a[112:127], v[76:79], v[84:87], a[112:127]
	v_mfma_f32_32x32x16_bf16 a[16:31], v[104:107], v[80:83], a[16:31]
	v_mfma_f32_32x32x16_bf16 a[0:15], v[104:107], v[84:87], a[0:15]
	s_add_u32 s44, s44, 0x80
	s_addc_u32 s45, s45, 0
	s_cmpk_lg_i32 s44, 0x700
	s_cbranch_scc1 xg5_varB_8
